# P0 weight transposes of w_in_a and w_in_b issue all 32 row loads before the first wait (were serialized in groups); nt hint on once-read weight rows, x in mod0 and in the fused GEMM2 epilogue
# speedup vs baseline: 1.0201x; 1.0117x over previous
.LBB0_7:
	s_waitcnt lgkmcnt(0)
	s_sub_i32 s2, 0, s2
	ds_read2_b32 v[102:103], v119 offset0:33 offset1:41
	ds_read2_b32 v[158:159], v119 offset1:8
	ds_read2_b32 v[160:161], v119 offset0:66 offset1:74
	ds_read2_b32 v[162:163], v119 offset0:99 offset1:107
	ds_read2_b32 v[164:165], v119 offset0:132 offset1:140
	ds_read2_b32 v[166:167], v119 offset0:165 offset1:173
	ds_read2_b32 v[168:169], v119 offset0:198 offset1:206
	ds_read2_b32 v[170:171], v119 offset0:231 offset1:239
	s_add_i32 s2, s2, s13
	v_add_u32_e32 v174, s2, v118
	s_ashr_i32 s7, s6, 31
	v_ashrrev_i32_e32 v175, 31, v174
	v_lshl_add_u64 v[172:173], s[6:7], 1, v[14:15]
	v_lshlrev_b64 v[176:177], 11, v[174:175]
	s_waitcnt lgkmcnt(6)
	v_cvt_pk_bf16_f32 v154, v158, v102
	s_waitcnt lgkmcnt(4)
	v_cvt_pk_bf16_f32 v155, v160, v162
	s_waitcnt lgkmcnt(2)
	v_cvt_pk_bf16_f32 v156, v164, v166
	s_waitcnt lgkmcnt(0)
	v_cvt_pk_bf16_f32 v157, v168, v170
	v_lshl_add_u64 v[176:177], v[172:173], 0, v[176:177]
	v_add_u32_e32 v102, 8, v174
	global_store_dwordx4 v[176:177], v[154:157], off
	s_nop 1
	v_cvt_pk_bf16_f32 v154, v159, v103
	v_ashrrev_i32_e32 v103, 31, v102
	v_cvt_pk_bf16_f32 v155, v161, v163
	v_cvt_pk_bf16_f32 v156, v165, v167
	v_cvt_pk_bf16_f32 v157, v169, v171
	v_lshlrev_b64 v[102:103], 11, v[102:103]
	ds_read2_b32 v[158:159], v119 offset0:49 offset1:57
	ds_read2_b32 v[160:161], v119 offset0:16 offset1:24
	ds_read2_b32 v[162:163], v119 offset0:82 offset1:90
	ds_read2_b32 v[164:165], v119 offset0:115 offset1:123
	ds_read2_b32 v[166:167], v119 offset0:148 offset1:156
	ds_read2_b32 v[168:169], v119 offset0:181 offset1:189
	ds_read2_b32 v[170:171], v119 offset0:214 offset1:222
	ds_read2_b32 v[176:177], v119 offset0:247 offset1:255
	v_lshl_add_u64 v[102:103], v[172:173], 0, v[102:103]
	global_store_dwordx4 v[102:103], v[154:157], off
	v_add_u32_e32 v102, 16, v174
	v_ashrrev_i32_e32 v103, 31, v102
	v_lshlrev_b64 v[102:103], 11, v[102:103]
	s_waitcnt lgkmcnt(6)
	v_cvt_pk_bf16_f32 v154, v160, v158
	s_waitcnt lgkmcnt(4)
	v_cvt_pk_bf16_f32 v155, v162, v164
	s_waitcnt lgkmcnt(2)
	v_cvt_pk_bf16_f32 v156, v166, v168
	s_waitcnt lgkmcnt(0)
	v_cvt_pk_bf16_f32 v157, v170, v176
	v_lshl_add_u64 v[102:103], v[172:173], 0, v[102:103]
	global_store_dwordx4 v[102:103], v[154:157], off
	v_add_u32_e32 v102, 24, v174
	v_ashrrev_i32_e32 v103, 31, v102
	v_lshlrev_b64 v[102:103], 11, v[102:103]
	v_cvt_pk_bf16_f32 v154, v161, v159
	v_cvt_pk_bf16_f32 v155, v163, v165
	v_cvt_pk_bf16_f32 v156, v167, v169
	v_cvt_pk_bf16_f32 v157, v171, v177
	v_lshl_add_u64 v[102:103], v[172:173], 0, v[102:103]
	global_store_dwordx4 v[102:103], v[154:157], off
	s_waitcnt lgkmcnt(0)

.LBB0_9:
	s_cmpk_gt_i32 s21, 0x3ff
	s_mov_b64 s[6:7], -1
	s_cbranch_scc0 .LBB0_95
	s_cmpk_gt_u32 s21, 0x5ff
	s_cbranch_scc0 .LBB0_92
	s_cmpk_gt_u32 s21, 0x8ff
	s_cbranch_scc0 .LBB0_89
	s_cmpk_gt_u32 s21, 0xd1f
	s_cbranch_scc0 .LBB0_54
	s_cmpk_gt_u32 s21, 0xf1f
	s_cbranch_scc0 .LBB0_51
	s_cmpk_gt_u32 s21, 0x111f
	s_cbranch_scc0 .LBB0_48
	s_and_saveexec_b64 s[6:7], s[4:5]
	s_xor_b64 s[6:7], exec, s[6:7]
	v_add_u32_e32 v4, v104, v153
	ds_write2_b32 v4, v5, v5 offset1:66
	s_or_saveexec_b64 s[6:7], s[6:7]
	s_add_i32 s2, s21, 0xffffeee0
	s_lshr_b32 s2, s2, 2
	s_lshl_b64 s[10:11], s[2:3], 15
	s_and_b32 s8, s13, 64
	v_lshl_add_u64 v[102:103], v[24:25], 0, s[10:11]
	v_mov_b32_e32 v4, 0
	v_mov_b32_e32 v37, 0
	s_xor_b64 exec, exec, s[6:7]
	s_cbranch_execz .LBB0_19
	v_or_b32_e32 v4, s8, v3
	v_lshlrev_b32_e32 v4, 8, v4
	v_lshl_add_u64 v[154:155], v[102:103], 0, v[4:5]
	v_or_b32_e32 v4, s8, v105
	v_lshlrev_b32_e32 v4, 8, v4
	v_lshl_add_u64 v[156:157], v[102:103], 0, v[4:5]
	v_or_b32_e32 v4, s8, v123
	v_lshlrev_b32_e32 v4, 8, v4
	v_lshl_add_u64 v[158:159], v[102:103], 0, v[4:5]
	v_or_b32_e32 v4, s8, v124
	v_lshlrev_b32_e32 v4, 8, v4
	v_lshl_add_u64 v[160:161], v[102:103], 0, v[4:5]
	global_load_dword v39, v[154:155], off nt
	global_load_dword v41, v[156:157], off nt
	global_load_dword v4, v[158:159], off nt
	global_load_dword v37, v[160:161], off nt
	v_add_u32_e32 v43, v104, v153
	s_waitcnt vmcnt(2)
	ds_write2_b32 v43, v39, v41 offset1:66
.LBB0_19:
	s_or_b64 exec, exec, s[6:7]
	v_add_u32_e32 v39, v104, v106
	s_waitcnt vmcnt(0)
	ds_write2_b32 v39, v4, v37 offset1:66
	s_and_saveexec_b64 s[6:7], s[4:5]
	s_xor_b64 s[6:7], exec, s[6:7]
	v_add_u32_e32 v4, v104, v107
	ds_write2_b32 v4, v5, v5 offset1:66
	s_or_saveexec_b64 s[6:7], s[6:7]
	v_mov_b32_e32 v4, 0
	v_mov_b32_e32 v37, 0
	s_xor_b64 exec, exec, s[6:7]
	s_cbranch_execz .LBB0_23
	v_or_b32_e32 v4, s8, v125
	v_lshlrev_b32_e32 v4, 8, v4
	v_lshl_add_u64 v[154:155], v[102:103], 0, v[4:5]
	v_or_b32_e32 v4, s8, v126
	v_lshlrev_b32_e32 v4, 8, v4
	v_lshl_add_u64 v[156:157], v[102:103], 0, v[4:5]
	v_or_b32_e32 v4, s8, v127
	v_lshlrev_b32_e32 v4, 8, v4
	v_lshl_add_u64 v[158:159], v[102:103], 0, v[4:5]
	v_or_b32_e32 v4, s8, v128
	v_lshlrev_b32_e32 v4, 8, v4
	v_lshl_add_u64 v[160:161], v[102:103], 0, v[4:5]
	global_load_dword v39, v[154:155], off nt
	global_load_dword v41, v[156:157], off nt
	global_load_dword v4, v[158:159], off nt
	global_load_dword v37, v[160:161], off nt
	v_add_u32_e32 v43, v104, v107
	s_waitcnt vmcnt(2)
	ds_write2_b32 v43, v39, v41 offset1:66
.LBB0_23:
	s_or_b64 exec, exec, s[6:7]
	v_add_u32_e32 v39, v104, v108
	s_waitcnt vmcnt(0)
	ds_write2_b32 v39, v4, v37 offset1:66
	s_and_saveexec_b64 s[6:7], s[4:5]
	s_xor_b64 s[6:7], exec, s[6:7]
	v_add_u32_e32 v4, v104, v109
	ds_write2_b32 v4, v5, v5 offset1:66
	s_or_saveexec_b64 s[6:7], s[6:7]
	v_mov_b32_e32 v4, 0
	v_mov_b32_e32 v37, 0
	s_xor_b64 exec, exec, s[6:7]
	s_cbranch_execz .LBB0_27
	v_or_b32_e32 v4, s8, v129
	v_lshlrev_b32_e32 v4, 8, v4
	v_lshl_add_u64 v[154:155], v[102:103], 0, v[4:5]
	v_or_b32_e32 v4, s8, v130
	v_lshlrev_b32_e32 v4, 8, v4
	v_lshl_add_u64 v[156:157], v[102:103], 0, v[4:5]
	v_or_b32_e32 v4, s8, v131
	v_lshlrev_b32_e32 v4, 8, v4
	v_lshl_add_u64 v[158:159], v[102:103], 0, v[4:5]
	v_or_b32_e32 v4, s8, v132
	v_lshlrev_b32_e32 v4, 8, v4
	v_lshl_add_u64 v[160:161], v[102:103], 0, v[4:5]
	global_load_dword v39, v[154:155], off nt
	global_load_dword v41, v[156:157], off nt
	global_load_dword v4, v[158:159], off nt
	global_load_dword v37, v[160:161], off nt
	v_add_u32_e32 v43, v104, v109
	s_waitcnt vmcnt(2)
	ds_write2_b32 v43, v39, v41 offset1:66
.LBB0_27:
	s_or_b64 exec, exec, s[6:7]
	v_add_u32_e32 v39, v104, v110
	s_waitcnt vmcnt(0)
	ds_write2_b32 v39, v4, v37 offset1:66
	s_and_saveexec_b64 s[6:7], s[4:5]
	s_xor_b64 s[6:7], exec, s[6:7]
	v_add_u32_e32 v4, v104, v111
	ds_write2_b32 v4, v5, v5 offset1:66
	s_or_saveexec_b64 s[6:7], s[6:7]
	v_mov_b32_e32 v4, 0
	v_mov_b32_e32 v37, 0
	s_xor_b64 exec, exec, s[6:7]
	s_cbranch_execz .LBB0_31
	v_or_b32_e32 v4, s8, v133
	v_lshlrev_b32_e32 v4, 8, v4
	v_lshl_add_u64 v[154:155], v[102:103], 0, v[4:5]
	v_or_b32_e32 v4, s8, v134
	v_lshlrev_b32_e32 v4, 8, v4
	v_lshl_add_u64 v[156:157], v[102:103], 0, v[4:5]
	v_or_b32_e32 v4, s8, v135
	v_lshlrev_b32_e32 v4, 8, v4
	v_lshl_add_u64 v[158:159], v[102:103], 0, v[4:5]
	v_or_b32_e32 v4, s8, v136
	v_lshlrev_b32_e32 v4, 8, v4
	v_lshl_add_u64 v[160:161], v[102:103], 0, v[4:5]
	global_load_dword v39, v[154:155], off nt
	global_load_dword v41, v[156:157], off nt
	global_load_dword v4, v[158:159], off nt
	global_load_dword v37, v[160:161], off nt
	v_add_u32_e32 v43, v104, v111
	s_waitcnt vmcnt(2)
	ds_write2_b32 v43, v39, v41 offset1:66
.LBB0_31:
	s_or_b64 exec, exec, s[6:7]
	v_add_u32_e32 v39, v104, v112
	s_waitcnt vmcnt(0)
	ds_write2_b32 v39, v4, v37 offset1:66
	s_and_saveexec_b64 s[6:7], s[4:5]
	s_xor_b64 s[6:7], exec, s[6:7]
	v_add_u32_e32 v4, v104, v113
	ds_write2_b32 v4, v5, v5 offset1:66
	s_or_saveexec_b64 s[6:7], s[6:7]
	v_mov_b32_e32 v4, 0
	v_mov_b32_e32 v37, 0
	s_xor_b64 exec, exec, s[6:7]
	s_cbranch_execz .LBB0_35
	v_or_b32_e32 v4, s8, v137
	v_lshlrev_b32_e32 v4, 8, v4
	v_lshl_add_u64 v[154:155], v[102:103], 0, v[4:5]
	v_or_b32_e32 v4, s8, v138
	v_lshlrev_b32_e32 v4, 8, v4
	v_lshl_add_u64 v[156:157], v[102:103], 0, v[4:5]
	v_or_b32_e32 v4, s8, v139
	v_lshlrev_b32_e32 v4, 8, v4
	v_lshl_add_u64 v[158:159], v[102:103], 0, v[4:5]
	v_or_b32_e32 v4, s8, v140
	v_lshlrev_b32_e32 v4, 8, v4
	v_lshl_add_u64 v[160:161], v[102:103], 0, v[4:5]
	global_load_dword v39, v[154:155], off nt
	global_load_dword v41, v[156:157], off nt
	global_load_dword v4, v[158:159], off nt
	global_load_dword v37, v[160:161], off nt
	v_add_u32_e32 v43, v104, v113
	s_waitcnt vmcnt(2)
	ds_write2_b32 v43, v39, v41 offset1:66
.LBB0_35:
	s_or_b64 exec, exec, s[6:7]
	v_add_u32_e32 v39, v104, v114
	s_waitcnt vmcnt(0)
	ds_write2_b32 v39, v4, v37 offset1:66
	s_and_saveexec_b64 s[6:7], s[4:5]
	s_xor_b64 s[6:7], exec, s[6:7]
	v_add_u32_e32 v4, v104, v115
	ds_write2_b32 v4, v5, v5 offset1:66
	s_or_saveexec_b64 s[6:7], s[6:7]
	v_mov_b32_e32 v4, 0
	v_mov_b32_e32 v37, 0
	s_xor_b64 exec, exec, s[6:7]
	s_cbranch_execz .LBB0_39
	v_or_b32_e32 v4, s8, v141
	v_lshlrev_b32_e32 v4, 8, v4
	v_lshl_add_u64 v[154:155], v[102:103], 0, v[4:5]
	v_or_b32_e32 v4, s8, v142
	v_lshlrev_b32_e32 v4, 8, v4
	v_lshl_add_u64 v[156:157], v[102:103], 0, v[4:5]
	v_or_b32_e32 v4, s8, v143
	v_lshlrev_b32_e32 v4, 8, v4
	v_lshl_add_u64 v[158:159], v[102:103], 0, v[4:5]
	v_or_b32_e32 v4, s8, v144
	v_lshlrev_b32_e32 v4, 8, v4
	v_lshl_add_u64 v[160:161], v[102:103], 0, v[4:5]
	global_load_dword v39, v[154:155], off nt
	global_load_dword v41, v[156:157], off nt
	global_load_dword v4, v[158:159], off nt
	global_load_dword v37, v[160:161], off nt
	v_add_u32_e32 v43, v104, v115
	s_waitcnt vmcnt(2)
	ds_write2_b32 v43, v39, v41 offset1:66
.LBB0_39:
	s_or_b64 exec, exec, s[6:7]
	v_add_u32_e32 v39, v104, v116
	s_waitcnt vmcnt(0)
	ds_write2_b32 v39, v4, v37 offset1:66
	s_and_saveexec_b64 s[6:7], s[4:5]
	s_xor_b64 s[6:7], exec, s[6:7]
	v_add_u32_e32 v4, v104, v117
	ds_write2_b32 v4, v5, v5 offset1:66
	s_or_saveexec_b64 s[6:7], s[6:7]
	v_mov_b32_e32 v4, 0
	v_mov_b32_e32 v37, 0
	s_xor_b64 exec, exec, s[6:7]
	s_cbranch_execz .LBB0_43
	v_or_b32_e32 v4, s8, v145
	v_lshlrev_b32_e32 v4, 8, v4
	v_lshl_add_u64 v[154:155], v[102:103], 0, v[4:5]
	v_or_b32_e32 v4, s8, v146
	v_lshlrev_b32_e32 v4, 8, v4
	v_lshl_add_u64 v[156:157], v[102:103], 0, v[4:5]
	v_or_b32_e32 v4, s8, v147
	v_lshlrev_b32_e32 v4, 8, v4
	v_lshl_add_u64 v[158:159], v[102:103], 0, v[4:5]
	v_or_b32_e32 v4, s8, v148
	v_lshlrev_b32_e32 v4, 8, v4
	v_lshl_add_u64 v[160:161], v[102:103], 0, v[4:5]
	global_load_dword v39, v[154:155], off nt
	global_load_dword v41, v[156:157], off nt
	global_load_dword v4, v[158:159], off nt
	global_load_dword v37, v[160:161], off nt
	v_add_u32_e32 v43, v104, v117
	s_waitcnt vmcnt(2)
	ds_write2_b32 v43, v39, v41 offset1:66
.LBB0_43:
	s_or_b64 exec, exec, s[6:7]
	v_add_u32_e32 v39, v104, v117
	s_waitcnt vmcnt(0)
	ds_write2_b32 v39, v4, v37 offset0:132 offset1:198
	v_add_u32_e32 v37, 0x400, v39
	s_and_saveexec_b64 s[6:7], s[4:5]
	s_xor_b64 s[6:7], exec, s[6:7]
	ds_write2_b32 v37, v5, v5 offset0:8 offset1:74
	s_or_saveexec_b64 s[6:7], s[6:7]
	v_mov_b32_e32 v4, 0
	v_mov_b32_e32 v39, 0
	s_xor_b64 exec, exec, s[6:7]
	s_cbranch_execz .LBB0_47
	v_or_b32_e32 v4, s8, v149
	v_lshlrev_b32_e32 v4, 8, v4
	v_lshl_add_u64 v[154:155], v[102:103], 0, v[4:5]
	v_or_b32_e32 v4, s8, v150
	v_lshlrev_b32_e32 v4, 8, v4
	v_lshl_add_u64 v[156:157], v[102:103], 0, v[4:5]
	v_or_b32_e32 v4, s8, v151
	v_lshlrev_b32_e32 v4, 8, v4
	v_lshl_add_u64 v[158:159], v[102:103], 0, v[4:5]
	v_or_b32_e32 v4, s8, v152
	v_lshlrev_b32_e32 v4, 8, v4
	v_lshl_add_u64 v[102:103], v[102:103], 0, v[4:5]
	global_load_dword v41, v[154:155], off nt
	global_load_dword v43, v[156:157], off nt
	global_load_dword v4, v[158:159], off nt
	global_load_dword v39, v[102:103], off nt
	s_waitcnt vmcnt(2)
	ds_write2_b32 v37, v41, v43 offset0:8 offset1:74

.LBB0_48:
	s_and_b64 vcc, exec, s[6:7]
	s_cbranch_vccz .LBB0_50
	s_load_dwordx16 s[36:51], s[0:1], 0xc0
	s_add_i32 s2, s21, 0xfffff0e0
	s_lshr_b32 s2, s2, 2
	s_lshl_b64 s[6:7], s[2:3], 15
	v_lshlrev_b32_e32 v4, 2, v2
	s_waitcnt lgkmcnt(0)
	s_add_u32 s8, s38, s6
	s_addc_u32 s9, s39, s7
	s_lshl_b64 s[6:7], s[2:3], 14
	s_and_b32 s2, s13, 0x60
	s_lshl_b32 s10, s2, 2
	s_add_u32 s8, s8, s10
	s_addc_u32 s9, s9, 0
	v_lshl_add_u64 v[102:103], s[8:9], 0, v[4:5]
	v_mov_b32_e32 v39, v5
	v_lshl_add_u64 v[154:155], v[102:103], 0, v[38:39]
	v_mov_b32_e32 v41, v5
	v_mov_b32_e32 v43, v5
	v_mov_b32_e32 v45, v5
	v_mov_b32_e32 v47, v5
	v_mov_b32_e32 v49, v5
	v_mov_b32_e32 v51, v5
	v_mov_b32_e32 v53, v5
	v_lshl_add_u64 v[156:157], v[102:103], 0, v[40:41]
	v_lshl_add_u64 v[158:159], v[102:103], 0, v[42:43]
	v_lshl_add_u64 v[160:161], v[102:103], 0, v[44:45]
	v_lshl_add_u64 v[162:163], v[102:103], 0, v[46:47]
	v_lshl_add_u64 v[164:165], v[102:103], 0, v[48:49]
	v_lshl_add_u64 v[166:167], v[102:103], 0, v[50:51]
	v_lshl_add_u64 v[168:169], v[102:103], 0, v[52:53]
	global_load_dword v4, v[154:155], off nt
	global_load_dword v37, v[156:157], off nt
	global_load_dword v39, v[158:159], off nt
	global_load_dword v41, v[160:161], off nt
	global_load_dword v43, v[162:163], off nt
	global_load_dword v45, v[164:165], off nt
	global_load_dword v47, v[166:167], off nt
	global_load_dword v49, v[168:169], off nt
	v_mov_b32_e32 v55, v5
	v_lshl_add_u64 v[154:155], v[102:103], 0, v[54:55]
	v_mov_b32_e32 v57, v5
	v_mov_b32_e32 v59, v5
	v_mov_b32_e32 v61, v5
	v_mov_b32_e32 v63, v5
	v_mov_b32_e32 v65, v5
	v_mov_b32_e32 v67, v5
	v_mov_b32_e32 v69, v5
	v_lshl_add_u64 v[156:157], v[102:103], 0, v[56:57]
	v_lshl_add_u64 v[158:159], v[102:103], 0, v[58:59]
	v_lshl_add_u64 v[160:161], v[102:103], 0, v[60:61]
	v_lshl_add_u64 v[162:163], v[102:103], 0, v[62:63]
	v_lshl_add_u64 v[164:165], v[102:103], 0, v[64:65]
	v_lshl_add_u64 v[166:167], v[102:103], 0, v[66:67]
	v_lshl_add_u64 v[168:169], v[102:103], 0, v[68:69]
	global_load_dword v51, v[154:155], off nt
	global_load_dword v53, v[156:157], off nt
	global_load_dword v55, v[158:159], off nt
	global_load_dword v57, v[160:161], off nt
	global_load_dword v59, v[162:163], off nt
	global_load_dword v61, v[164:165], off nt
	global_load_dword v63, v[166:167], off nt
	global_load_dword v65, v[168:169], off nt
	v_mov_b32_e32 v71, v5
	v_lshl_add_u64 v[154:155], v[102:103], 0, v[70:71]
	v_mov_b32_e32 v73, v5
	v_mov_b32_e32 v75, v5
	v_mov_b32_e32 v77, v5
	v_mov_b32_e32 v79, v5
	v_mov_b32_e32 v81, v5
	v_mov_b32_e32 v83, v5
	v_mov_b32_e32 v85, v5
	v_lshl_add_u64 v[156:157], v[102:103], 0, v[72:73]
	v_lshl_add_u64 v[158:159], v[102:103], 0, v[74:75]
	v_lshl_add_u64 v[160:161], v[102:103], 0, v[76:77]
	v_lshl_add_u64 v[162:163], v[102:103], 0, v[78:79]
	v_lshl_add_u64 v[164:165], v[102:103], 0, v[80:81]
	v_lshl_add_u64 v[166:167], v[102:103], 0, v[82:83]
	v_lshl_add_u64 v[168:169], v[102:103], 0, v[84:85]
	global_load_dword v67, v[154:155], off nt
	global_load_dword v69, v[156:157], off nt
	global_load_dword v71, v[158:159], off nt
	global_load_dword v73, v[160:161], off nt
	global_load_dword v75, v[162:163], off nt
	global_load_dword v77, v[164:165], off nt
	global_load_dword v79, v[166:167], off nt
	global_load_dword v81, v[168:169], off nt
	v_mov_b32_e32 v87, v5
	v_lshl_add_u64 v[154:155], v[102:103], 0, v[86:87]
	v_mov_b32_e32 v89, v5
	v_mov_b32_e32 v91, v5
	v_mov_b32_e32 v93, v5
	v_mov_b32_e32 v95, v5
	v_mov_b32_e32 v97, v5
	v_mov_b32_e32 v99, v5
	v_mov_b32_e32 v101, v5
	v_lshl_add_u64 v[156:157], v[102:103], 0, v[88:89]
	v_lshl_add_u64 v[158:159], v[102:103], 0, v[90:91]
	v_lshl_add_u64 v[160:161], v[102:103], 0, v[92:93]
	v_lshl_add_u64 v[162:163], v[102:103], 0, v[94:95]
	v_lshl_add_u64 v[164:165], v[102:103], 0, v[96:97]
	v_lshl_add_u64 v[166:167], v[102:103], 0, v[98:99]
	v_lshl_add_u64 v[102:103], v[102:103], 0, v[100:101]
	global_load_dword v83, v[154:155], off nt
	global_load_dword v85, v[156:157], off nt
	global_load_dword v87, v[158:159], off nt
	global_load_dword v89, v[160:161], off nt
	global_load_dword v91, v[162:163], off nt
	global_load_dword v93, v[164:165], off nt
	global_load_dword v95, v[166:167], off nt
	global_load_dword v97, v[102:103], off nt
	v_add_u32_e32 v99, v104, v153
	v_lshl_add_u64 v[172:173], v[6:7], 0, s[6:7]
	s_waitcnt vmcnt(30)
	ds_write2_b32 v99, v4, v37 offset1:66
	s_waitcnt vmcnt(28)
	ds_write2_b32 v99, v39, v41 offset0:132 offset1:198
	v_add_u32_e32 v4, 0x400, v99
	s_waitcnt vmcnt(26)
	ds_write2_b32 v4, v43, v45 offset0:8 offset1:74
	v_add_u32_e32 v4, v104, v108
	s_waitcnt vmcnt(24)
	ds_write2_b32 v4, v47, v49 offset1:66
	s_waitcnt vmcnt(22)
	ds_write2_b32 v4, v51, v53 offset0:132 offset1:198
	v_add_u32_e32 v4, 0x400, v4
	s_waitcnt vmcnt(20)
	ds_write2_b32 v4, v55, v57 offset0:8 offset1:74
	v_add_u32_e32 v4, v104, v111
	s_waitcnt vmcnt(18)
	ds_write2_b32 v4, v59, v61 offset1:66
	s_waitcnt vmcnt(16)
	ds_write2_b32 v4, v63, v65 offset0:132 offset1:198
	v_add_u32_e32 v4, 0x400, v4
	s_waitcnt vmcnt(14)
	ds_write2_b32 v4, v67, v69 offset0:8 offset1:74
	v_add_u32_e32 v4, v104, v114
	s_waitcnt vmcnt(12)
	ds_write2_b32 v4, v71, v73 offset1:66
	s_waitcnt vmcnt(10)
	ds_write2_b32 v4, v75, v77 offset0:132 offset1:198
	v_add_u32_e32 v4, 0x400, v4
	s_waitcnt vmcnt(8)
	ds_write2_b32 v4, v79, v81 offset0:8 offset1:74
	v_add_u32_e32 v4, v104, v117
	s_waitcnt vmcnt(6)
	ds_write2_b32 v4, v83, v85 offset1:66
	s_waitcnt vmcnt(4)
	ds_write2_b32 v4, v87, v89 offset0:132 offset1:198
	v_add_u32_e32 v4, 0x400, v4
	s_waitcnt vmcnt(2)
	ds_write2_b32 v4, v91, v93 offset0:8 offset1:74
	s_waitcnt vmcnt(0)
	ds_write2_b32 v4, v95, v97 offset0:140 offset1:206
	s_waitcnt lgkmcnt(0)
	ds_read2_b32 v[102:103], v119 offset0:33 offset1:41
	ds_read2_b32 v[158:159], v119 offset1:8
	ds_read2_b32 v[160:161], v119 offset0:66 offset1:74
	ds_read2_b32 v[162:163], v119 offset0:99 offset1:107
	ds_read2_b32 v[164:165], v119 offset0:132 offset1:140
	ds_read2_b32 v[166:167], v119 offset0:165 offset1:173
	ds_read2_b32 v[168:169], v119 offset0:198 offset1:206
	ds_read2_b32 v[170:171], v119 offset0:231 offset1:239
	v_or_b32_e32 v4, s2, v118
	v_lshlrev_b32_e32 v4, 7, v4
	s_waitcnt lgkmcnt(6)
	v_cvt_pk_bf16_f32 v154, v158, v102
	s_waitcnt lgkmcnt(4)
	v_cvt_pk_bf16_f32 v155, v160, v162
	s_waitcnt lgkmcnt(2)
	v_cvt_pk_bf16_f32 v156, v164, v166
	s_waitcnt lgkmcnt(0)
	v_cvt_pk_bf16_f32 v157, v168, v170
	v_lshl_add_u64 v[174:175], v[172:173], 0, v[4:5]
	global_store_dwordx4 v[174:175], v[154:157], off
	v_or_b32_e32 v4, s2, v120
	v_lshlrev_b32_e32 v4, 7, v4
	v_cvt_pk_bf16_f32 v154, v159, v103
	v_cvt_pk_bf16_f32 v155, v161, v163
	v_cvt_pk_bf16_f32 v156, v165, v167
	v_cvt_pk_bf16_f32 v157, v169, v171
	ds_read2_b32 v[158:159], v119 offset0:49 offset1:57
	ds_read2_b32 v[160:161], v119 offset0:16 offset1:24
	ds_read2_b32 v[162:163], v119 offset0:82 offset1:90
	ds_read2_b32 v[164:165], v119 offset0:115 offset1:123
	ds_read2_b32 v[166:167], v119 offset0:148 offset1:156
	ds_read2_b32 v[168:169], v119 offset0:181 offset1:189
	ds_read2_b32 v[170:171], v119 offset0:214 offset1:222
	ds_read2_b32 v[174:175], v119 offset0:247 offset1:255
	v_lshl_add_u64 v[102:103], v[172:173], 0, v[4:5]
	v_or_b32_e32 v4, s2, v121
	v_lshlrev_b32_e32 v4, 7, v4
	global_store_dwordx4 v[102:103], v[154:157], off
	v_lshl_add_u64 v[102:103], v[172:173], 0, v[4:5]
	v_or_b32_e32 v4, s2, v122
	s_waitcnt lgkmcnt(6)
	v_cvt_pk_bf16_f32 v154, v160, v158
	s_waitcnt lgkmcnt(4)
	v_cvt_pk_bf16_f32 v155, v162, v164
	s_waitcnt lgkmcnt(2)
	v_cvt_pk_bf16_f32 v156, v166, v168
	s_waitcnt lgkmcnt(0)
	v_cvt_pk_bf16_f32 v157, v170, v174
	v_lshlrev_b32_e32 v4, 7, v4
	global_store_dwordx4 v[102:103], v[154:157], off
	v_lshl_add_u64 v[102:103], v[172:173], 0, v[4:5]
	s_nop 0
	v_cvt_pk_bf16_f32 v154, v161, v159
	v_cvt_pk_bf16_f32 v155, v163, v165
	v_cvt_pk_bf16_f32 v156, v167, v169
	v_cvt_pk_bf16_f32 v157, v171, v175
	global_store_dwordx4 v[102:103], v[154:157], off
	s_waitcnt lgkmcnt(0)

.LBB0_51:
	s_andn2_b64 vcc, exec, s[6:7]
	s_cbranch_vccnz .LBB0_53
	s_and_b32 s7, s15, 0x1ffc0
	s_and_b32 s6, s13, 0x3e0
	s_lshl_b32 s2, s6, 2
	v_or_b32_e32 v4, s7, v3
	v_lshl_add_u64 v[102:103], v[26:27], 0, s[2:3]
	v_lshlrev_b32_e32 v4, 12, v4
	v_lshl_add_u64 v[154:155], v[102:103], 0, v[4:5]
	v_or_b32_e32 v4, s7, v105
	v_lshlrev_b32_e32 v4, 12, v4
	v_lshl_add_u64 v[156:157], v[102:103], 0, v[4:5]
	v_or_b32_e32 v4, s7, v123
	v_lshlrev_b32_e32 v4, 12, v4
	v_lshl_add_u64 v[158:159], v[102:103], 0, v[4:5]
	v_or_b32_e32 v4, s7, v124
	v_lshlrev_b32_e32 v4, 12, v4
	v_lshl_add_u64 v[160:161], v[102:103], 0, v[4:5]
	v_or_b32_e32 v4, s7, v125
	v_lshlrev_b32_e32 v4, 12, v4
	v_lshl_add_u64 v[162:163], v[102:103], 0, v[4:5]
	v_or_b32_e32 v4, s7, v126
	v_lshlrev_b32_e32 v4, 12, v4
	v_lshl_add_u64 v[164:165], v[102:103], 0, v[4:5]
	v_or_b32_e32 v4, s7, v127
	v_lshlrev_b32_e32 v4, 12, v4
	v_lshl_add_u64 v[166:167], v[102:103], 0, v[4:5]
	v_or_b32_e32 v4, s7, v128
	v_lshlrev_b32_e32 v4, 12, v4
	v_lshl_add_u64 v[168:169], v[102:103], 0, v[4:5]
	v_or_b32_e32 v4, s7, v129
	v_lshlrev_b32_e32 v4, 12, v4
	global_load_dword v37, v[154:155], off nt
	global_load_dword v39, v[156:157], off nt
	global_load_dword v41, v[158:159], off nt
	global_load_dword v43, v[160:161], off nt
	global_load_dword v45, v[162:163], off nt
	global_load_dword v47, v[164:165], off nt
	global_load_dword v49, v[166:167], off nt
	global_load_dword v51, v[168:169], off nt
	v_lshl_add_u64 v[154:155], v[102:103], 0, v[4:5]
	v_or_b32_e32 v4, s7, v130
	v_lshlrev_b32_e32 v4, 12, v4
	v_lshl_add_u64 v[156:157], v[102:103], 0, v[4:5]
	v_or_b32_e32 v4, s7, v131
	v_lshlrev_b32_e32 v4, 12, v4
	v_lshl_add_u64 v[158:159], v[102:103], 0, v[4:5]
	v_or_b32_e32 v4, s7, v132
	v_lshlrev_b32_e32 v4, 12, v4
	v_lshl_add_u64 v[160:161], v[102:103], 0, v[4:5]
	v_or_b32_e32 v4, s7, v133
	v_lshlrev_b32_e32 v4, 12, v4
	v_lshl_add_u64 v[162:163], v[102:103], 0, v[4:5]
	v_or_b32_e32 v4, s7, v134
	v_lshlrev_b32_e32 v4, 12, v4
	v_lshl_add_u64 v[164:165], v[102:103], 0, v[4:5]
	v_or_b32_e32 v4, s7, v135
	v_lshlrev_b32_e32 v4, 12, v4
	v_lshl_add_u64 v[166:167], v[102:103], 0, v[4:5]
	v_or_b32_e32 v4, s7, v136
	v_lshlrev_b32_e32 v4, 12, v4
	v_lshl_add_u64 v[168:169], v[102:103], 0, v[4:5]
	v_or_b32_e32 v4, s7, v137
	v_lshlrev_b32_e32 v4, 12, v4
	global_load_dword v53, v[154:155], off nt
	global_load_dword v55, v[156:157], off nt
	global_load_dword v57, v[158:159], off nt
	global_load_dword v59, v[160:161], off nt
	global_load_dword v61, v[162:163], off nt
	global_load_dword v63, v[164:165], off nt
	global_load_dword v65, v[166:167], off nt
	global_load_dword v67, v[168:169], off nt
	v_lshl_add_u64 v[154:155], v[102:103], 0, v[4:5]
	v_or_b32_e32 v4, s7, v138
	v_lshlrev_b32_e32 v4, 12, v4
	v_lshl_add_u64 v[156:157], v[102:103], 0, v[4:5]
	v_or_b32_e32 v4, s7, v139
	v_lshlrev_b32_e32 v4, 12, v4
	v_lshl_add_u64 v[158:159], v[102:103], 0, v[4:5]
	v_or_b32_e32 v4, s7, v140
	v_lshlrev_b32_e32 v4, 12, v4
	v_lshl_add_u64 v[160:161], v[102:103], 0, v[4:5]
	v_or_b32_e32 v4, s7, v141
	v_lshlrev_b32_e32 v4, 12, v4
	v_lshl_add_u64 v[162:163], v[102:103], 0, v[4:5]
	v_or_b32_e32 v4, s7, v142
	v_lshlrev_b32_e32 v4, 12, v4
	v_lshl_add_u64 v[164:165], v[102:103], 0, v[4:5]
	v_or_b32_e32 v4, s7, v143
	v_lshlrev_b32_e32 v4, 12, v4
	v_lshl_add_u64 v[166:167], v[102:103], 0, v[4:5]
	v_or_b32_e32 v4, s7, v144
	v_lshlrev_b32_e32 v4, 12, v4
	v_lshl_add_u64 v[168:169], v[102:103], 0, v[4:5]
	v_or_b32_e32 v4, s7, v145
	v_lshlrev_b32_e32 v4, 12, v4
	global_load_dword v69, v[154:155], off nt
	global_load_dword v71, v[156:157], off nt
	global_load_dword v73, v[158:159], off nt
	global_load_dword v75, v[160:161], off nt
	global_load_dword v77, v[162:163], off nt
	global_load_dword v79, v[164:165], off nt
	global_load_dword v81, v[166:167], off nt
	global_load_dword v83, v[168:169], off nt
	v_lshl_add_u64 v[154:155], v[102:103], 0, v[4:5]
	v_or_b32_e32 v4, s7, v146
	v_lshlrev_b32_e32 v4, 12, v4
	v_lshl_add_u64 v[156:157], v[102:103], 0, v[4:5]
	v_or_b32_e32 v4, s7, v147
	v_lshlrev_b32_e32 v4, 12, v4
	v_lshl_add_u64 v[158:159], v[102:103], 0, v[4:5]
	v_or_b32_e32 v4, s7, v148
	v_lshlrev_b32_e32 v4, 12, v4
	v_lshl_add_u64 v[160:161], v[102:103], 0, v[4:5]
	v_or_b32_e32 v4, s7, v149
	v_lshlrev_b32_e32 v4, 12, v4
	v_lshl_add_u64 v[162:163], v[102:103], 0, v[4:5]
	v_or_b32_e32 v4, s7, v150
	v_lshlrev_b32_e32 v4, 12, v4
	v_lshl_add_u64 v[164:165], v[102:103], 0, v[4:5]
	v_or_b32_e32 v4, s7, v151
	v_lshlrev_b32_e32 v4, 12, v4
	v_lshl_add_u64 v[166:167], v[102:103], 0, v[4:5]
	v_or_b32_e32 v4, s7, v152
	v_lshlrev_b32_e32 v4, 12, v4
	v_lshl_add_u64 v[102:103], v[102:103], 0, v[4:5]
	global_load_dword v4, v[154:155], off nt
	global_load_dword v85, v[156:157], off nt
	global_load_dword v87, v[158:159], off nt
	global_load_dword v89, v[160:161], off nt
	global_load_dword v91, v[162:163], off nt
	global_load_dword v93, v[164:165], off nt
	global_load_dword v95, v[166:167], off nt
	global_load_dword v97, v[102:103], off nt
	v_add_u32_e32 v99, v104, v153
	s_waitcnt vmcnt(30)
	ds_write2_b32 v99, v37, v39 offset1:66
	s_waitcnt vmcnt(28)
	ds_write2_b32 v99, v41, v43 offset0:132 offset1:198
	v_add_u32_e32 v37, 0x400, v99
	s_waitcnt vmcnt(26)
	ds_write2_b32 v37, v45, v47 offset0:8 offset1:74
	v_add_u32_e32 v37, v104, v108
	s_waitcnt vmcnt(24)
	ds_write2_b32 v37, v49, v51 offset1:66
	s_waitcnt vmcnt(22)
	ds_write2_b32 v37, v53, v55 offset0:132 offset1:198
	v_add_u32_e32 v37, 0x400, v37
	s_waitcnt vmcnt(20)
	ds_write2_b32 v37, v57, v59 offset0:8 offset1:74
	v_add_u32_e32 v37, v104, v111
	s_waitcnt vmcnt(18)
	ds_write2_b32 v37, v61, v63 offset1:66
	s_waitcnt vmcnt(16)
	ds_write2_b32 v37, v65, v67 offset0:132 offset1:198
	v_add_u32_e32 v37, 0x400, v37
	s_lshl_b32 s2, s7, 1
	v_lshl_add_u64 v[172:173], v[8:9], 0, s[2:3]
	s_waitcnt vmcnt(14)
	ds_write2_b32 v37, v69, v71 offset0:8 offset1:74
	v_add_u32_e32 v37, v104, v114
	s_waitcnt vmcnt(12)
	ds_write2_b32 v37, v73, v75 offset1:66
	s_waitcnt vmcnt(10)
	ds_write2_b32 v37, v77, v79 offset0:132 offset1:198
	v_add_u32_e32 v37, 0x400, v37
	s_waitcnt vmcnt(8)
	ds_write2_b32 v37, v81, v83 offset0:8 offset1:74
	v_add_u32_e32 v37, v104, v117
	s_waitcnt vmcnt(6)
	ds_write2_b32 v37, v4, v85 offset1:66
	s_waitcnt vmcnt(4)
	ds_write2_b32 v37, v87, v89 offset0:132 offset1:198
	v_add_u32_e32 v4, 0x400, v37
	s_waitcnt vmcnt(2)
	ds_write2_b32 v4, v91, v93 offset0:8 offset1:74
	s_waitcnt vmcnt(0)
	ds_write2_b32 v4, v95, v97 offset0:140 offset1:206
	s_waitcnt lgkmcnt(0)
	ds_read2_b32 v[102:103], v119 offset0:33 offset1:41
	ds_read2_b32 v[158:159], v119 offset1:8
	ds_read2_b32 v[160:161], v119 offset0:66 offset1:74
	ds_read2_b32 v[162:163], v119 offset0:99 offset1:107
	ds_read2_b32 v[164:165], v119 offset0:132 offset1:140
	ds_read2_b32 v[166:167], v119 offset0:165 offset1:173
	ds_read2_b32 v[168:169], v119 offset0:198 offset1:206
	ds_read2_b32 v[170:171], v119 offset0:231 offset1:239
	v_or_b32_e32 v4, s6, v118
	v_lshlrev_b32_e32 v4, 11, v4
	s_waitcnt lgkmcnt(6)
	v_cvt_pk_bf16_f32 v154, v158, v102
	s_waitcnt lgkmcnt(4)
	v_cvt_pk_bf16_f32 v155, v160, v162
	s_waitcnt lgkmcnt(2)
	v_cvt_pk_bf16_f32 v156, v164, v166
	s_waitcnt lgkmcnt(0)
	v_cvt_pk_bf16_f32 v157, v168, v170
	v_lshl_add_u64 v[174:175], v[172:173], 0, v[4:5]
	global_store_dwordx4 v[174:175], v[154:157], off
	v_or_b32_e32 v4, s6, v120
	v_lshlrev_b32_e32 v4, 11, v4
	v_cvt_pk_bf16_f32 v154, v159, v103
	v_cvt_pk_bf16_f32 v155, v161, v163
	v_cvt_pk_bf16_f32 v156, v165, v167
	v_cvt_pk_bf16_f32 v157, v169, v171
	ds_read2_b32 v[158:159], v119 offset0:49 offset1:57
	ds_read2_b32 v[160:161], v119 offset0:16 offset1:24
	ds_read2_b32 v[162:163], v119 offset0:82 offset1:90
	ds_read2_b32 v[164:165], v119 offset0:115 offset1:123
	ds_read2_b32 v[166:167], v119 offset0:148 offset1:156
	ds_read2_b32 v[168:169], v119 offset0:181 offset1:189
	ds_read2_b32 v[170:171], v119 offset0:214 offset1:222
	ds_read2_b32 v[174:175], v119 offset0:247 offset1:255
	v_lshl_add_u64 v[102:103], v[172:173], 0, v[4:5]
	v_or_b32_e32 v4, s6, v121
	v_lshlrev_b32_e32 v4, 11, v4
	global_store_dwordx4 v[102:103], v[154:157], off
	v_lshl_add_u64 v[102:103], v[172:173], 0, v[4:5]
	v_or_b32_e32 v4, s6, v122
	s_waitcnt lgkmcnt(6)
	v_cvt_pk_bf16_f32 v154, v160, v158
	s_waitcnt lgkmcnt(4)
	v_cvt_pk_bf16_f32 v155, v162, v164
	s_waitcnt lgkmcnt(2)
	v_cvt_pk_bf16_f32 v156, v166, v168
	s_waitcnt lgkmcnt(0)
	v_cvt_pk_bf16_f32 v157, v170, v174
	v_lshlrev_b32_e32 v4, 11, v4
	global_store_dwordx4 v[102:103], v[154:157], off
	v_lshl_add_u64 v[102:103], v[172:173], 0, v[4:5]
	s_nop 0
	v_cvt_pk_bf16_f32 v154, v161, v159
	v_cvt_pk_bf16_f32 v155, v163, v165
	v_cvt_pk_bf16_f32 v156, v167, v169
	v_cvt_pk_bf16_f32 v157, v171, v175
	global_store_dwordx4 v[102:103], v[154:157], off
	s_waitcnt lgkmcnt(0)

.LBB0_54:
	s_andn2_b64 vcc, exec, s[6:7]
	s_cbranch_vccnz .LBB0_88
	s_add_i32 s6, s21, 0xf700
	s_and_b32 s2, s6, 0xffff
	s_mul_i32 s2, s2, 0xf83f
	s_lshr_b32 s7, s2, 22
	s_mulk_i32 s7, 0x42
	s_sub_i32 s6, s6, s7
	s_lshl_b32 s6, s6, 5
	s_and_b32 s8, s6, 0xffe0
	v_or_b32_e32 v4, s8, v2
	v_cmp_lt_u32_e32 vcc, s17, v4
	s_lshr_b32 s2, s2, 16
	s_and_b32 s9, s2, 0xffc0
	s_lshl_b32 s2, s8, 2
	v_lshl_add_u64 v[102:103], v[28:29], 0, s[2:3]
	v_mov_b32_e32 v37, 0
	v_mov_b32_e32 v39, 0
	v_mov_b32_e32 v41, 0
	v_mov_b32_e32 v43, 0
	v_mov_b32_e32 v45, 0
	v_mov_b32_e32 v47, 0
	v_mov_b32_e32 v49, 0
	v_mov_b32_e32 v51, 0
	v_mov_b32_e32 v53, 0
	v_mov_b32_e32 v55, 0
	v_mov_b32_e32 v57, 0
	v_mov_b32_e32 v59, 0
	v_mov_b32_e32 v61, 0
	v_mov_b32_e32 v63, 0
	v_mov_b32_e32 v65, 0
	v_mov_b32_e32 v67, 0
	v_mov_b32_e32 v69, 0
	v_mov_b32_e32 v71, 0
	v_mov_b32_e32 v73, 0
	v_mov_b32_e32 v75, 0
	v_mov_b32_e32 v77, 0
	v_mov_b32_e32 v79, 0
	v_mov_b32_e32 v81, 0
	v_mov_b32_e32 v83, 0
	v_mov_b32_e32 v4, 0
	v_mov_b32_e32 v85, 0
	v_mov_b32_e32 v87, 0
	v_mov_b32_e32 v89, 0
	v_mov_b32_e32 v91, 0
	v_mov_b32_e32 v93, 0
	v_mov_b32_e32 v95, 0
	v_mov_b32_e32 v97, 0
	s_mov_b64 s[6:7], exec
	s_andn2_b64 exec, exec, vcc
	v_or_b32_e32 v4, s9, v3
	v_mul_u32_u24_e32 v4, 0x830, v4
	v_lshlrev_b32_e32 v4, 2, v4
	v_lshl_add_u64 v[154:155], v[102:103], 0, v[4:5]
	v_or_b32_e32 v4, s9, v105
	v_mul_u32_u24_e32 v4, 0x830, v4
	v_lshlrev_b32_e32 v4, 2, v4
	v_lshl_add_u64 v[156:157], v[102:103], 0, v[4:5]
	v_or_b32_e32 v4, s9, v123
	v_mul_u32_u24_e32 v4, 0x830, v4
	v_lshlrev_b32_e32 v4, 2, v4
	v_lshl_add_u64 v[158:159], v[102:103], 0, v[4:5]
	v_or_b32_e32 v4, s9, v124
	v_mul_u32_u24_e32 v4, 0x830, v4
	v_lshlrev_b32_e32 v4, 2, v4
	v_lshl_add_u64 v[160:161], v[102:103], 0, v[4:5]
	v_or_b32_e32 v4, s9, v125
	v_mul_u32_u24_e32 v4, 0x830, v4
	v_lshlrev_b32_e32 v4, 2, v4
	v_lshl_add_u64 v[162:163], v[102:103], 0, v[4:5]
	v_or_b32_e32 v4, s9, v126
	v_mul_u32_u24_e32 v4, 0x830, v4
	v_lshlrev_b32_e32 v4, 2, v4
	v_lshl_add_u64 v[164:165], v[102:103], 0, v[4:5]
	v_or_b32_e32 v4, s9, v127
	v_mul_u32_u24_e32 v4, 0x830, v4
	v_lshlrev_b32_e32 v4, 2, v4
	v_lshl_add_u64 v[166:167], v[102:103], 0, v[4:5]
	v_or_b32_e32 v4, s9, v128
	v_mul_u32_u24_e32 v4, 0x830, v4
	v_lshlrev_b32_e32 v4, 2, v4
	v_lshl_add_u64 v[168:169], v[102:103], 0, v[4:5]
	global_load_dword v37, v[154:155], off nt
	global_load_dword v39, v[156:157], off nt
	global_load_dword v41, v[158:159], off nt
	global_load_dword v43, v[160:161], off nt
	global_load_dword v45, v[162:163], off nt
	global_load_dword v47, v[164:165], off nt
	global_load_dword v49, v[166:167], off nt
	global_load_dword v51, v[168:169], off nt
	v_or_b32_e32 v4, s9, v129
	v_mul_u32_u24_e32 v4, 0x830, v4
	v_lshlrev_b32_e32 v4, 2, v4
	v_lshl_add_u64 v[154:155], v[102:103], 0, v[4:5]
	v_or_b32_e32 v4, s9, v130
	v_mul_u32_u24_e32 v4, 0x830, v4
	v_lshlrev_b32_e32 v4, 2, v4
	v_lshl_add_u64 v[156:157], v[102:103], 0, v[4:5]
	v_or_b32_e32 v4, s9, v131
	v_mul_u32_u24_e32 v4, 0x830, v4
	v_lshlrev_b32_e32 v4, 2, v4
	v_lshl_add_u64 v[158:159], v[102:103], 0, v[4:5]
	v_or_b32_e32 v4, s9, v132
	v_mul_u32_u24_e32 v4, 0x830, v4
	v_lshlrev_b32_e32 v4, 2, v4
	v_lshl_add_u64 v[160:161], v[102:103], 0, v[4:5]
	v_or_b32_e32 v4, s9, v133
	v_mul_u32_u24_e32 v4, 0x830, v4
	v_lshlrev_b32_e32 v4, 2, v4
	v_lshl_add_u64 v[162:163], v[102:103], 0, v[4:5]
	v_or_b32_e32 v4, s9, v134
	v_mul_u32_u24_e32 v4, 0x830, v4
	v_lshlrev_b32_e32 v4, 2, v4
	v_lshl_add_u64 v[164:165], v[102:103], 0, v[4:5]
	v_or_b32_e32 v4, s9, v135
	v_mul_u32_u24_e32 v4, 0x830, v4
	v_lshlrev_b32_e32 v4, 2, v4
	v_lshl_add_u64 v[166:167], v[102:103], 0, v[4:5]
	v_or_b32_e32 v4, s9, v136
	v_mul_u32_u24_e32 v4, 0x830, v4
	v_lshlrev_b32_e32 v4, 2, v4
	v_lshl_add_u64 v[168:169], v[102:103], 0, v[4:5]
	global_load_dword v53, v[154:155], off nt
	global_load_dword v55, v[156:157], off nt
	global_load_dword v57, v[158:159], off nt
	global_load_dword v59, v[160:161], off nt
	global_load_dword v61, v[162:163], off nt
	global_load_dword v63, v[164:165], off nt
	global_load_dword v65, v[166:167], off nt
	global_load_dword v67, v[168:169], off nt
	v_or_b32_e32 v4, s9, v137
	v_mul_u32_u24_e32 v4, 0x830, v4
	v_lshlrev_b32_e32 v4, 2, v4
	v_lshl_add_u64 v[154:155], v[102:103], 0, v[4:5]
	v_or_b32_e32 v4, s9, v138
	v_mul_u32_u24_e32 v4, 0x830, v4
	v_lshlrev_b32_e32 v4, 2, v4
	v_lshl_add_u64 v[156:157], v[102:103], 0, v[4:5]
	v_or_b32_e32 v4, s9, v139
	v_mul_u32_u24_e32 v4, 0x830, v4
	v_lshlrev_b32_e32 v4, 2, v4
	v_lshl_add_u64 v[158:159], v[102:103], 0, v[4:5]
	v_or_b32_e32 v4, s9, v140
	v_mul_u32_u24_e32 v4, 0x830, v4
	v_lshlrev_b32_e32 v4, 2, v4
	v_lshl_add_u64 v[160:161], v[102:103], 0, v[4:5]
	v_or_b32_e32 v4, s9, v141
	v_mul_u32_u24_e32 v4, 0x830, v4
	v_lshlrev_b32_e32 v4, 2, v4
	v_lshl_add_u64 v[162:163], v[102:103], 0, v[4:5]
	v_or_b32_e32 v4, s9, v142
	v_mul_u32_u24_e32 v4, 0x830, v4
	v_lshlrev_b32_e32 v4, 2, v4
	v_lshl_add_u64 v[164:165], v[102:103], 0, v[4:5]
	v_or_b32_e32 v4, s9, v143
	v_mul_u32_u24_e32 v4, 0x830, v4
	v_lshlrev_b32_e32 v4, 2, v4
	v_lshl_add_u64 v[166:167], v[102:103], 0, v[4:5]
	v_or_b32_e32 v4, s9, v144
	v_mul_u32_u24_e32 v4, 0x830, v4
	v_lshlrev_b32_e32 v4, 2, v4
	v_lshl_add_u64 v[168:169], v[102:103], 0, v[4:5]
	global_load_dword v69, v[154:155], off nt
	global_load_dword v71, v[156:157], off nt
	global_load_dword v73, v[158:159], off nt
	global_load_dword v75, v[160:161], off nt
	global_load_dword v77, v[162:163], off nt
	global_load_dword v79, v[164:165], off nt
	global_load_dword v81, v[166:167], off nt
	global_load_dword v83, v[168:169], off nt
	v_or_b32_e32 v4, s9, v145
	v_mul_u32_u24_e32 v4, 0x830, v4
	v_lshlrev_b32_e32 v4, 2, v4
	v_lshl_add_u64 v[154:155], v[102:103], 0, v[4:5]
	v_or_b32_e32 v4, s9, v146
	v_mul_u32_u24_e32 v4, 0x830, v4
	v_lshlrev_b32_e32 v4, 2, v4
	v_lshl_add_u64 v[156:157], v[102:103], 0, v[4:5]
	v_or_b32_e32 v4, s9, v147
	v_mul_u32_u24_e32 v4, 0x830, v4
	v_lshlrev_b32_e32 v4, 2, v4
	v_lshl_add_u64 v[158:159], v[102:103], 0, v[4:5]
	v_or_b32_e32 v4, s9, v148
	v_mul_u32_u24_e32 v4, 0x830, v4
	v_lshlrev_b32_e32 v4, 2, v4
	v_lshl_add_u64 v[160:161], v[102:103], 0, v[4:5]
	v_or_b32_e32 v4, s9, v149
	v_mul_u32_u24_e32 v4, 0x830, v4
	v_lshlrev_b32_e32 v4, 2, v4
	v_lshl_add_u64 v[162:163], v[102:103], 0, v[4:5]
	v_or_b32_e32 v4, s9, v150
	v_mul_u32_u24_e32 v4, 0x830, v4
	v_lshlrev_b32_e32 v4, 2, v4
	v_lshl_add_u64 v[164:165], v[102:103], 0, v[4:5]
	v_or_b32_e32 v4, s9, v151
	v_mul_u32_u24_e32 v4, 0x830, v4
	v_lshlrev_b32_e32 v4, 2, v4
	v_lshl_add_u64 v[166:167], v[102:103], 0, v[4:5]
	v_or_b32_e32 v4, s9, v152
	v_mul_u32_u24_e32 v4, 0x830, v4
	v_lshlrev_b32_e32 v4, 2, v4
	v_lshl_add_u64 v[168:169], v[102:103], 0, v[4:5]
	global_load_dword v4, v[154:155], off nt
	global_load_dword v85, v[156:157], off nt
	global_load_dword v87, v[158:159], off nt
	global_load_dword v89, v[160:161], off nt
	global_load_dword v91, v[162:163], off nt
	global_load_dword v93, v[164:165], off nt
	global_load_dword v95, v[166:167], off nt
	global_load_dword v97, v[168:169], off nt
	s_mov_b64 exec, s[6:7]
	v_add_u32_e32 v99, v104, v153
	s_waitcnt vmcnt(30)
	ds_write2_b32 v99, v37, v39 offset1:66
	s_waitcnt vmcnt(28)
	ds_write2_b32 v99, v41, v43 offset0:132 offset1:198
	v_add_u32_e32 v37, 0x400, v99
	s_waitcnt vmcnt(26)
	ds_write2_b32 v37, v45, v47 offset0:8 offset1:74
	v_add_u32_e32 v37, v104, v108
	s_waitcnt vmcnt(24)
	ds_write2_b32 v37, v49, v51 offset1:66
	s_waitcnt vmcnt(22)
	ds_write2_b32 v37, v53, v55 offset0:132 offset1:198
	v_add_u32_e32 v37, 0x400, v37
	s_waitcnt vmcnt(20)
	ds_write2_b32 v37, v57, v59 offset0:8 offset1:74
	v_add_u32_e32 v37, v104, v111
	s_waitcnt vmcnt(18)
	ds_write2_b32 v37, v61, v63 offset1:66
	s_waitcnt vmcnt(16)
	ds_write2_b32 v37, v65, v67 offset0:132 offset1:198
	v_add_u32_e32 v37, 0x400, v37
	s_waitcnt vmcnt(14)
	ds_write2_b32 v37, v69, v71 offset0:8 offset1:74
	v_add_u32_e32 v37, v104, v114
	s_waitcnt vmcnt(12)
	ds_write2_b32 v37, v73, v75 offset1:66
	s_waitcnt vmcnt(10)
	ds_write2_b32 v37, v77, v79 offset0:132 offset1:198
	v_add_u32_e32 v37, 0x400, v37
	s_waitcnt vmcnt(8)
	ds_write2_b32 v37, v81, v83 offset0:8 offset1:74
	v_add_u32_e32 v37, v104, v117
	s_waitcnt vmcnt(6)
	ds_write2_b32 v37, v4, v85 offset1:66
	s_waitcnt vmcnt(4)
	ds_write2_b32 v37, v87, v89 offset0:132 offset1:198
	v_add_u32_e32 v4, 0x400, v37
	s_waitcnt vmcnt(2)
	ds_write2_b32 v4, v91, v93 offset0:8 offset1:74
	s_waitcnt vmcnt(0)
	ds_write2_b32 v4, v95, v97 offset0:140 offset1:206
	s_waitcnt lgkmcnt(0)
	ds_read2_b32 v[102:103], v119 offset0:33 offset1:41
	ds_read2_b32 v[158:159], v119 offset1:8
	ds_read2_b32 v[160:161], v119 offset0:66 offset1:74
	ds_read2_b32 v[162:163], v119 offset0:99 offset1:107
	ds_read2_b32 v[164:165], v119 offset0:132 offset1:140
	ds_read2_b32 v[166:167], v119 offset0:165 offset1:173
	ds_read2_b32 v[168:169], v119 offset0:198 offset1:206
	ds_read2_b32 v[170:171], v119 offset0:231 offset1:239
	s_addk_i32 s8, 0x600
	s_lshl_b32 s2, s9, 1
	v_or_b32_e32 v4, s8, v118
	v_lshl_add_u64 v[172:173], v[10:11], 0, s[2:3]
	v_lshlrev_b32_e32 v4, 11, v4
	s_waitcnt lgkmcnt(6)
	v_cvt_pk_bf16_f32 v154, v158, v102
	s_waitcnt lgkmcnt(4)
	v_cvt_pk_bf16_f32 v155, v160, v162
	s_waitcnt lgkmcnt(2)
	v_cvt_pk_bf16_f32 v156, v164, v166
	s_waitcnt lgkmcnt(0)
	v_cvt_pk_bf16_f32 v157, v168, v170
	v_lshl_add_u64 v[174:175], v[172:173], 0, v[4:5]
	global_store_dwordx4 v[174:175], v[154:157], off
	v_or_b32_e32 v4, s8, v120
	v_lshlrev_b32_e32 v4, 11, v4
	v_cvt_pk_bf16_f32 v154, v159, v103
	v_cvt_pk_bf16_f32 v155, v161, v163
	v_cvt_pk_bf16_f32 v156, v165, v167
	v_cvt_pk_bf16_f32 v157, v169, v171
	ds_read2_b32 v[158:159], v119 offset0:49 offset1:57
	ds_read2_b32 v[160:161], v119 offset0:16 offset1:24
	ds_read2_b32 v[162:163], v119 offset0:82 offset1:90
	ds_read2_b32 v[164:165], v119 offset0:115 offset1:123
	ds_read2_b32 v[166:167], v119 offset0:148 offset1:156
	ds_read2_b32 v[168:169], v119 offset0:181 offset1:189
	ds_read2_b32 v[170:171], v119 offset0:214 offset1:222
	ds_read2_b32 v[174:175], v119 offset0:247 offset1:255
	v_lshl_add_u64 v[102:103], v[172:173], 0, v[4:5]
	v_or_b32_e32 v4, s8, v121
	v_lshlrev_b32_e32 v4, 11, v4
	global_store_dwordx4 v[102:103], v[154:157], off
	v_lshl_add_u64 v[102:103], v[172:173], 0, v[4:5]
	v_or_b32_e32 v4, s8, v122
	s_waitcnt lgkmcnt(6)
	v_cvt_pk_bf16_f32 v154, v160, v158
	s_waitcnt lgkmcnt(4)
	v_cvt_pk_bf16_f32 v155, v162, v164
	s_waitcnt lgkmcnt(2)
	v_cvt_pk_bf16_f32 v156, v166, v168
	s_waitcnt lgkmcnt(0)
	v_cvt_pk_bf16_f32 v157, v170, v174
	v_lshlrev_b32_e32 v4, 11, v4
	global_store_dwordx4 v[102:103], v[154:157], off
	v_lshl_add_u64 v[102:103], v[172:173], 0, v[4:5]
	s_nop 0
	v_cvt_pk_bf16_f32 v154, v161, v159
	v_cvt_pk_bf16_f32 v155, v163, v165
	v_cvt_pk_bf16_f32 v156, v167, v169
	v_cvt_pk_bf16_f32 v157, v171, v175
	global_store_dwordx4 v[102:103], v[154:157], off
	s_waitcnt lgkmcnt(0)

.LBB0_89:
	s_andn2_b64 vcc, exec, s[6:7]
	s_cbranch_vccnz .LBB0_91
	s_add_i32 s2, s21, 0xfa00
	s_and_b32 s6, s2, 0xffff
	s_mul_i32 s6, s6, 0xaaab
	s_lshr_b32 s7, s6, 21
	s_mul_i32 s6, s7, 48
	s_sub_i32 s2, s2, s6
	s_lshl_b32 s8, s7, 6
	s_lshl_b32 s2, s2, 5
	s_and_b32 s6, s2, 0xffe0
	v_or_b32_e32 v4, s8, v3
	s_lshl_b32 s2, s6, 2
	v_mul_u32_u24_e32 v4, 0x600, v4
	v_lshl_add_u64 v[102:103], v[30:31], 0, s[2:3]
	v_lshlrev_b32_e32 v4, 2, v4
	v_lshl_add_u64 v[154:155], v[102:103], 0, v[4:5]
	v_or_b32_e32 v4, s8, v105
	v_mul_u32_u24_e32 v4, 0x600, v4
	v_lshlrev_b32_e32 v4, 2, v4
	v_lshl_add_u64 v[156:157], v[102:103], 0, v[4:5]
	v_or_b32_e32 v4, s8, v123
	v_mul_u32_u24_e32 v4, 0x600, v4
	v_lshlrev_b32_e32 v4, 2, v4
	v_lshl_add_u64 v[158:159], v[102:103], 0, v[4:5]
	v_or_b32_e32 v4, s8, v124
	v_mul_u32_u24_e32 v4, 0x600, v4
	v_lshlrev_b32_e32 v4, 2, v4
	v_lshl_add_u64 v[160:161], v[102:103], 0, v[4:5]
	v_or_b32_e32 v4, s8, v125
	v_mul_u32_u24_e32 v4, 0x600, v4
	v_lshlrev_b32_e32 v4, 2, v4
	v_lshl_add_u64 v[162:163], v[102:103], 0, v[4:5]
	v_or_b32_e32 v4, s8, v126
	v_mul_u32_u24_e32 v4, 0x600, v4
	v_lshlrev_b32_e32 v4, 2, v4
	v_lshl_add_u64 v[164:165], v[102:103], 0, v[4:5]
	v_or_b32_e32 v4, s8, v127
	v_mul_u32_u24_e32 v4, 0x600, v4
	v_lshlrev_b32_e32 v4, 2, v4
	v_lshl_add_u64 v[166:167], v[102:103], 0, v[4:5]
	v_or_b32_e32 v4, s8, v128
	v_mul_u32_u24_e32 v4, 0x600, v4
	v_lshlrev_b32_e32 v4, 2, v4
	v_lshl_add_u64 v[168:169], v[102:103], 0, v[4:5]
	v_or_b32_e32 v4, s8, v129
	v_mul_u32_u24_e32 v4, 0x600, v4
	v_lshlrev_b32_e32 v4, 2, v4
	global_load_dword v37, v[154:155], off nt
	global_load_dword v39, v[156:157], off nt
	global_load_dword v41, v[158:159], off nt
	global_load_dword v43, v[160:161], off nt
	global_load_dword v45, v[162:163], off nt
	global_load_dword v47, v[164:165], off nt
	global_load_dword v49, v[166:167], off nt
	global_load_dword v51, v[168:169], off nt
	v_lshl_add_u64 v[154:155], v[102:103], 0, v[4:5]
	v_or_b32_e32 v4, s8, v130
	v_mul_u32_u24_e32 v4, 0x600, v4
	v_lshlrev_b32_e32 v4, 2, v4
	v_lshl_add_u64 v[156:157], v[102:103], 0, v[4:5]
	v_or_b32_e32 v4, s8, v131
	v_mul_u32_u24_e32 v4, 0x600, v4
	v_lshlrev_b32_e32 v4, 2, v4
	v_lshl_add_u64 v[158:159], v[102:103], 0, v[4:5]
	v_or_b32_e32 v4, s8, v132
	v_mul_u32_u24_e32 v4, 0x600, v4
	v_lshlrev_b32_e32 v4, 2, v4
	v_lshl_add_u64 v[160:161], v[102:103], 0, v[4:5]
	v_or_b32_e32 v4, s8, v133
	v_mul_u32_u24_e32 v4, 0x600, v4
	v_lshlrev_b32_e32 v4, 2, v4
	v_lshl_add_u64 v[162:163], v[102:103], 0, v[4:5]
	v_or_b32_e32 v4, s8, v134
	v_mul_u32_u24_e32 v4, 0x600, v4
	v_lshlrev_b32_e32 v4, 2, v4
	v_lshl_add_u64 v[164:165], v[102:103], 0, v[4:5]
	v_or_b32_e32 v4, s8, v135
	v_mul_u32_u24_e32 v4, 0x600, v4
	v_lshlrev_b32_e32 v4, 2, v4
	v_lshl_add_u64 v[166:167], v[102:103], 0, v[4:5]
	v_or_b32_e32 v4, s8, v136
	v_mul_u32_u24_e32 v4, 0x600, v4
	v_lshlrev_b32_e32 v4, 2, v4
	v_lshl_add_u64 v[168:169], v[102:103], 0, v[4:5]
	v_or_b32_e32 v4, s8, v137
	v_mul_u32_u24_e32 v4, 0x600, v4
	v_lshlrev_b32_e32 v4, 2, v4
	global_load_dword v53, v[154:155], off nt
	global_load_dword v55, v[156:157], off nt
	global_load_dword v57, v[158:159], off nt
	global_load_dword v59, v[160:161], off nt
	global_load_dword v61, v[162:163], off nt
	global_load_dword v63, v[164:165], off nt
	global_load_dword v65, v[166:167], off nt
	global_load_dword v67, v[168:169], off nt
	v_lshl_add_u64 v[154:155], v[102:103], 0, v[4:5]
	v_or_b32_e32 v4, s8, v138
	v_mul_u32_u24_e32 v4, 0x600, v4
	v_lshlrev_b32_e32 v4, 2, v4
	v_lshl_add_u64 v[156:157], v[102:103], 0, v[4:5]
	v_or_b32_e32 v4, s8, v139
	v_mul_u32_u24_e32 v4, 0x600, v4
	v_lshlrev_b32_e32 v4, 2, v4
	v_lshl_add_u64 v[158:159], v[102:103], 0, v[4:5]
	v_or_b32_e32 v4, s8, v140
	v_mul_u32_u24_e32 v4, 0x600, v4
	v_lshlrev_b32_e32 v4, 2, v4
	v_lshl_add_u64 v[160:161], v[102:103], 0, v[4:5]
	v_or_b32_e32 v4, s8, v141
	v_mul_u32_u24_e32 v4, 0x600, v4
	v_lshlrev_b32_e32 v4, 2, v4
	v_lshl_add_u64 v[162:163], v[102:103], 0, v[4:5]
	v_or_b32_e32 v4, s8, v142
	v_mul_u32_u24_e32 v4, 0x600, v4
	v_lshlrev_b32_e32 v4, 2, v4
	v_lshl_add_u64 v[164:165], v[102:103], 0, v[4:5]
	v_or_b32_e32 v4, s8, v143
	v_mul_u32_u24_e32 v4, 0x600, v4
	v_lshlrev_b32_e32 v4, 2, v4
	v_lshl_add_u64 v[166:167], v[102:103], 0, v[4:5]
	v_or_b32_e32 v4, s8, v144
	v_mul_u32_u24_e32 v4, 0x600, v4
	v_lshlrev_b32_e32 v4, 2, v4
	v_lshl_add_u64 v[168:169], v[102:103], 0, v[4:5]
	v_or_b32_e32 v4, s8, v145
	v_mul_u32_u24_e32 v4, 0x600, v4
	v_lshlrev_b32_e32 v4, 2, v4
	global_load_dword v69, v[154:155], off nt
	global_load_dword v71, v[156:157], off nt
	global_load_dword v73, v[158:159], off nt
	global_load_dword v75, v[160:161], off nt
	global_load_dword v77, v[162:163], off nt
	global_load_dword v79, v[164:165], off nt
	global_load_dword v81, v[166:167], off nt
	global_load_dword v83, v[168:169], off nt
	v_lshl_add_u64 v[154:155], v[102:103], 0, v[4:5]
	v_or_b32_e32 v4, s8, v146
	v_mul_u32_u24_e32 v4, 0x600, v4
	v_lshlrev_b32_e32 v4, 2, v4
	v_lshl_add_u64 v[156:157], v[102:103], 0, v[4:5]
	v_or_b32_e32 v4, s8, v147
	v_mul_u32_u24_e32 v4, 0x600, v4
	v_lshlrev_b32_e32 v4, 2, v4
	v_lshl_add_u64 v[158:159], v[102:103], 0, v[4:5]
	v_or_b32_e32 v4, s8, v148
	v_mul_u32_u24_e32 v4, 0x600, v4
	v_lshlrev_b32_e32 v4, 2, v4
	v_lshl_add_u64 v[160:161], v[102:103], 0, v[4:5]
	v_or_b32_e32 v4, s8, v149
	v_mul_u32_u24_e32 v4, 0x600, v4
	v_lshlrev_b32_e32 v4, 2, v4
	v_lshl_add_u64 v[162:163], v[102:103], 0, v[4:5]
	v_or_b32_e32 v4, s8, v150
	v_mul_u32_u24_e32 v4, 0x600, v4
	v_lshlrev_b32_e32 v4, 2, v4
	v_lshl_add_u64 v[164:165], v[102:103], 0, v[4:5]
	v_or_b32_e32 v4, s8, v151
	v_mul_u32_u24_e32 v4, 0x600, v4
	v_lshlrev_b32_e32 v4, 2, v4
	v_lshl_add_u64 v[166:167], v[102:103], 0, v[4:5]
	v_or_b32_e32 v4, s8, v152
	v_mul_u32_u24_e32 v4, 0x600, v4
	v_lshlrev_b32_e32 v4, 2, v4
	v_lshl_add_u64 v[102:103], v[102:103], 0, v[4:5]
	global_load_dword v4, v[154:155], off nt
	global_load_dword v85, v[156:157], off nt
	global_load_dword v87, v[158:159], off nt
	global_load_dword v89, v[160:161], off nt
	global_load_dword v91, v[162:163], off nt
	global_load_dword v93, v[164:165], off nt
	global_load_dword v95, v[166:167], off nt
	global_load_dword v97, v[102:103], off nt
	v_add_u32_e32 v99, v104, v153
	s_waitcnt vmcnt(30)
	ds_write2_b32 v99, v37, v39 offset1:66
	s_waitcnt vmcnt(28)
	ds_write2_b32 v99, v41, v43 offset0:132 offset1:198
	v_add_u32_e32 v37, 0x400, v99
	s_waitcnt vmcnt(26)
	ds_write2_b32 v37, v45, v47 offset0:8 offset1:74
	v_add_u32_e32 v37, v104, v108
	s_waitcnt vmcnt(24)
	ds_write2_b32 v37, v49, v51 offset1:66
	s_waitcnt vmcnt(22)
	ds_write2_b32 v37, v53, v55 offset0:132 offset1:198
	v_add_u32_e32 v37, 0x400, v37
	s_waitcnt vmcnt(20)
	ds_write2_b32 v37, v57, v59 offset0:8 offset1:74
	v_add_u32_e32 v37, v104, v111
	s_waitcnt vmcnt(18)
	ds_write2_b32 v37, v61, v63 offset1:66
	s_waitcnt vmcnt(16)
	ds_write2_b32 v37, v65, v67 offset0:132 offset1:198
	v_add_u32_e32 v37, 0x400, v37
	s_lshl_b32 s2, s7, 7
	v_lshl_add_u64 v[172:173], v[10:11], 0, s[2:3]
	s_waitcnt vmcnt(14)
	ds_write2_b32 v37, v69, v71 offset0:8 offset1:74
	v_add_u32_e32 v37, v104, v114
	s_waitcnt vmcnt(12)
	ds_write2_b32 v37, v73, v75 offset1:66
	s_waitcnt vmcnt(10)
	ds_write2_b32 v37, v77, v79 offset0:132 offset1:198
	v_add_u32_e32 v37, 0x400, v37
	s_waitcnt vmcnt(8)
	ds_write2_b32 v37, v81, v83 offset0:8 offset1:74
	v_add_u32_e32 v37, v104, v117
	s_waitcnt vmcnt(6)
	ds_write2_b32 v37, v4, v85 offset1:66
	s_waitcnt vmcnt(4)
	ds_write2_b32 v37, v87, v89 offset0:132 offset1:198
	v_add_u32_e32 v4, 0x400, v37
	s_waitcnt vmcnt(2)
	ds_write2_b32 v4, v91, v93 offset0:8 offset1:74
	s_waitcnt vmcnt(0)
	ds_write2_b32 v4, v95, v97 offset0:140 offset1:206
	s_waitcnt lgkmcnt(0)
	ds_read2_b32 v[102:103], v119 offset0:33 offset1:41
	ds_read2_b32 v[158:159], v119 offset1:8
	ds_read2_b32 v[160:161], v119 offset0:66 offset1:74
	ds_read2_b32 v[162:163], v119 offset0:99 offset1:107
	ds_read2_b32 v[164:165], v119 offset0:132 offset1:140
	ds_read2_b32 v[166:167], v119 offset0:165 offset1:173
	ds_read2_b32 v[168:169], v119 offset0:198 offset1:206
	ds_read2_b32 v[170:171], v119 offset0:231 offset1:239
	v_or_b32_e32 v4, s6, v118
	v_lshlrev_b32_e32 v4, 11, v4
	s_waitcnt lgkmcnt(6)
	v_cvt_pk_bf16_f32 v154, v158, v102
	s_waitcnt lgkmcnt(4)
	v_cvt_pk_bf16_f32 v155, v160, v162
	s_waitcnt lgkmcnt(2)
	v_cvt_pk_bf16_f32 v156, v164, v166
	s_waitcnt lgkmcnt(0)
	v_cvt_pk_bf16_f32 v157, v168, v170
	v_lshl_add_u64 v[174:175], v[172:173], 0, v[4:5]
	global_store_dwordx4 v[174:175], v[154:157], off
	v_or_b32_e32 v4, s6, v120
	v_lshlrev_b32_e32 v4, 11, v4
	v_cvt_pk_bf16_f32 v154, v159, v103
	v_cvt_pk_bf16_f32 v155, v161, v163
	v_cvt_pk_bf16_f32 v156, v165, v167
	v_cvt_pk_bf16_f32 v157, v169, v171
	ds_read2_b32 v[158:159], v119 offset0:49 offset1:57
	ds_read2_b32 v[160:161], v119 offset0:16 offset1:24
	ds_read2_b32 v[162:163], v119 offset0:82 offset1:90
	ds_read2_b32 v[164:165], v119 offset0:115 offset1:123
	ds_read2_b32 v[166:167], v119 offset0:148 offset1:156
	ds_read2_b32 v[168:169], v119 offset0:181 offset1:189
	ds_read2_b32 v[170:171], v119 offset0:214 offset1:222
	ds_read2_b32 v[174:175], v119 offset0:247 offset1:255
	v_lshl_add_u64 v[102:103], v[172:173], 0, v[4:5]
	v_or_b32_e32 v4, s6, v121
	v_lshlrev_b32_e32 v4, 11, v4
	global_store_dwordx4 v[102:103], v[154:157], off
	v_lshl_add_u64 v[102:103], v[172:173], 0, v[4:5]
	v_or_b32_e32 v4, s6, v122
	s_waitcnt lgkmcnt(6)
	v_cvt_pk_bf16_f32 v154, v160, v158
	s_waitcnt lgkmcnt(4)
	v_cvt_pk_bf16_f32 v155, v162, v164
	s_waitcnt lgkmcnt(2)
	v_cvt_pk_bf16_f32 v156, v166, v168
	s_waitcnt lgkmcnt(0)
	v_cvt_pk_bf16_f32 v157, v170, v174
	v_lshlrev_b32_e32 v4, 11, v4
	global_store_dwordx4 v[102:103], v[154:157], off
	v_lshl_add_u64 v[102:103], v[172:173], 0, v[4:5]
	s_nop 0
	v_cvt_pk_bf16_f32 v154, v161, v159
	v_cvt_pk_bf16_f32 v155, v163, v165
	v_cvt_pk_bf16_f32 v156, v167, v169
	v_cvt_pk_bf16_f32 v157, v171, v175
	global_store_dwordx4 v[102:103], v[154:157], off
	s_waitcnt lgkmcnt(0)

.LBB0_92:
	s_andn2_b64 vcc, exec, s[6:7]
	s_cbranch_vccnz .LBB0_94
	s_add_i32 s2, s15, 0x1240
	s_and_b32 s7, s2, 0x1ffc0
	s_and_b32 s6, s13, 0x3e0
	s_lshl_b32 s2, s6, 2
	v_or_b32_e32 v4, s7, v3
	v_lshl_add_u64 v[102:103], v[32:33], 0, s[2:3]
	v_lshlrev_b32_e32 v4, 12, v4
	v_lshl_add_u64 v[154:155], v[102:103], 0, v[4:5]
	v_or_b32_e32 v4, s7, v105
	v_lshlrev_b32_e32 v4, 12, v4
	v_lshl_add_u64 v[156:157], v[102:103], 0, v[4:5]
	v_or_b32_e32 v4, s7, v123
	v_lshlrev_b32_e32 v4, 12, v4
	v_lshl_add_u64 v[158:159], v[102:103], 0, v[4:5]
	v_or_b32_e32 v4, s7, v124
	v_lshlrev_b32_e32 v4, 12, v4
	v_lshl_add_u64 v[160:161], v[102:103], 0, v[4:5]
	v_or_b32_e32 v4, s7, v125
	v_lshlrev_b32_e32 v4, 12, v4
	v_lshl_add_u64 v[162:163], v[102:103], 0, v[4:5]
	v_or_b32_e32 v4, s7, v126
	v_lshlrev_b32_e32 v4, 12, v4
	v_lshl_add_u64 v[164:165], v[102:103], 0, v[4:5]
	v_or_b32_e32 v4, s7, v127
	v_lshlrev_b32_e32 v4, 12, v4
	v_lshl_add_u64 v[166:167], v[102:103], 0, v[4:5]
	v_or_b32_e32 v4, s7, v128
	v_lshlrev_b32_e32 v4, 12, v4
	v_lshl_add_u64 v[168:169], v[102:103], 0, v[4:5]
	v_or_b32_e32 v4, s7, v129
	v_lshlrev_b32_e32 v4, 12, v4
	global_load_dword v37, v[154:155], off nt
	global_load_dword v39, v[156:157], off nt
	global_load_dword v41, v[158:159], off nt
	global_load_dword v43, v[160:161], off nt
	global_load_dword v45, v[162:163], off nt
	global_load_dword v47, v[164:165], off nt
	global_load_dword v49, v[166:167], off nt
	global_load_dword v51, v[168:169], off nt
	v_lshl_add_u64 v[154:155], v[102:103], 0, v[4:5]
	v_or_b32_e32 v4, s7, v130
	v_lshlrev_b32_e32 v4, 12, v4
	v_lshl_add_u64 v[156:157], v[102:103], 0, v[4:5]
	v_or_b32_e32 v4, s7, v131
	v_lshlrev_b32_e32 v4, 12, v4
	v_lshl_add_u64 v[158:159], v[102:103], 0, v[4:5]
	v_or_b32_e32 v4, s7, v132
	v_lshlrev_b32_e32 v4, 12, v4
	v_lshl_add_u64 v[160:161], v[102:103], 0, v[4:5]
	v_or_b32_e32 v4, s7, v133
	v_lshlrev_b32_e32 v4, 12, v4
	v_lshl_add_u64 v[162:163], v[102:103], 0, v[4:5]
	v_or_b32_e32 v4, s7, v134
	v_lshlrev_b32_e32 v4, 12, v4
	v_lshl_add_u64 v[164:165], v[102:103], 0, v[4:5]
	v_or_b32_e32 v4, s7, v135
	v_lshlrev_b32_e32 v4, 12, v4
	v_lshl_add_u64 v[166:167], v[102:103], 0, v[4:5]
	v_or_b32_e32 v4, s7, v136
	v_lshlrev_b32_e32 v4, 12, v4
	v_lshl_add_u64 v[168:169], v[102:103], 0, v[4:5]
	v_or_b32_e32 v4, s7, v137
	v_lshlrev_b32_e32 v4, 12, v4
	global_load_dword v53, v[154:155], off nt
	global_load_dword v55, v[156:157], off nt
	global_load_dword v57, v[158:159], off nt
	global_load_dword v59, v[160:161], off nt
	global_load_dword v61, v[162:163], off nt
	global_load_dword v63, v[164:165], off nt
	global_load_dword v65, v[166:167], off nt
	global_load_dword v67, v[168:169], off nt
	v_lshl_add_u64 v[154:155], v[102:103], 0, v[4:5]
	v_or_b32_e32 v4, s7, v138
	v_lshlrev_b32_e32 v4, 12, v4
	v_lshl_add_u64 v[156:157], v[102:103], 0, v[4:5]
	v_or_b32_e32 v4, s7, v139
	v_lshlrev_b32_e32 v4, 12, v4
	v_lshl_add_u64 v[158:159], v[102:103], 0, v[4:5]
	v_or_b32_e32 v4, s7, v140
	v_lshlrev_b32_e32 v4, 12, v4
	v_lshl_add_u64 v[160:161], v[102:103], 0, v[4:5]
	v_or_b32_e32 v4, s7, v141
	v_lshlrev_b32_e32 v4, 12, v4
	v_lshl_add_u64 v[162:163], v[102:103], 0, v[4:5]
	v_or_b32_e32 v4, s7, v142
	v_lshlrev_b32_e32 v4, 12, v4
	v_lshl_add_u64 v[164:165], v[102:103], 0, v[4:5]
	v_or_b32_e32 v4, s7, v143
	v_lshlrev_b32_e32 v4, 12, v4
	v_lshl_add_u64 v[166:167], v[102:103], 0, v[4:5]
	v_or_b32_e32 v4, s7, v144
	v_lshlrev_b32_e32 v4, 12, v4
	v_lshl_add_u64 v[168:169], v[102:103], 0, v[4:5]
	v_or_b32_e32 v4, s7, v145
	v_lshlrev_b32_e32 v4, 12, v4
	global_load_dword v69, v[154:155], off nt
	global_load_dword v71, v[156:157], off nt
	global_load_dword v73, v[158:159], off nt
	global_load_dword v75, v[160:161], off nt
	global_load_dword v77, v[162:163], off nt
	global_load_dword v79, v[164:165], off nt
	global_load_dword v81, v[166:167], off nt
	global_load_dword v83, v[168:169], off nt
	v_lshl_add_u64 v[154:155], v[102:103], 0, v[4:5]
	v_or_b32_e32 v4, s7, v146
	v_lshlrev_b32_e32 v4, 12, v4
	v_lshl_add_u64 v[156:157], v[102:103], 0, v[4:5]
	v_or_b32_e32 v4, s7, v147
	v_lshlrev_b32_e32 v4, 12, v4
	v_lshl_add_u64 v[158:159], v[102:103], 0, v[4:5]
	v_or_b32_e32 v4, s7, v148
	v_lshlrev_b32_e32 v4, 12, v4
	v_lshl_add_u64 v[160:161], v[102:103], 0, v[4:5]
	v_or_b32_e32 v4, s7, v149
	v_lshlrev_b32_e32 v4, 12, v4
	v_lshl_add_u64 v[162:163], v[102:103], 0, v[4:5]
	v_or_b32_e32 v4, s7, v150
	v_lshlrev_b32_e32 v4, 12, v4
	v_lshl_add_u64 v[164:165], v[102:103], 0, v[4:5]
	v_or_b32_e32 v4, s7, v151
	v_lshlrev_b32_e32 v4, 12, v4
	v_lshl_add_u64 v[166:167], v[102:103], 0, v[4:5]
	v_or_b32_e32 v4, s7, v152
	v_lshlrev_b32_e32 v4, 12, v4
	v_lshl_add_u64 v[102:103], v[102:103], 0, v[4:5]
	global_load_dword v4, v[154:155], off nt
	global_load_dword v85, v[156:157], off nt
	global_load_dword v87, v[158:159], off nt
	global_load_dword v89, v[160:161], off nt
	global_load_dword v91, v[162:163], off nt
	global_load_dword v93, v[164:165], off nt
	global_load_dword v95, v[166:167], off nt
	global_load_dword v97, v[102:103], off nt
	v_add_u32_e32 v99, v104, v153
	s_waitcnt vmcnt(30)
	ds_write2_b32 v99, v37, v39 offset1:66
	s_waitcnt vmcnt(28)
	ds_write2_b32 v99, v41, v43 offset0:132 offset1:198
	v_add_u32_e32 v37, 0x400, v99
	s_waitcnt vmcnt(26)
	ds_write2_b32 v37, v45, v47 offset0:8 offset1:74
	v_add_u32_e32 v37, v104, v108
	s_waitcnt vmcnt(24)
	ds_write2_b32 v37, v49, v51 offset1:66
	s_waitcnt vmcnt(22)
	ds_write2_b32 v37, v53, v55 offset0:132 offset1:198
	v_add_u32_e32 v37, 0x400, v37
	s_waitcnt vmcnt(20)
	ds_write2_b32 v37, v57, v59 offset0:8 offset1:74
	v_add_u32_e32 v37, v104, v111
	s_waitcnt vmcnt(18)
	ds_write2_b32 v37, v61, v63 offset1:66
	s_waitcnt vmcnt(16)
	ds_write2_b32 v37, v65, v67 offset0:132 offset1:198
	v_add_u32_e32 v37, 0x400, v37
	s_lshl_b32 s2, s7, 1
	v_lshl_add_u64 v[172:173], v[12:13], 0, s[2:3]
	s_waitcnt vmcnt(14)
	ds_write2_b32 v37, v69, v71 offset0:8 offset1:74
	v_add_u32_e32 v37, v104, v114
	s_waitcnt vmcnt(12)
	ds_write2_b32 v37, v73, v75 offset1:66
	s_waitcnt vmcnt(10)
	ds_write2_b32 v37, v77, v79 offset0:132 offset1:198
	v_add_u32_e32 v37, 0x400, v37
	s_waitcnt vmcnt(8)
	ds_write2_b32 v37, v81, v83 offset0:8 offset1:74
	v_add_u32_e32 v37, v104, v117
	s_waitcnt vmcnt(6)
	ds_write2_b32 v37, v4, v85 offset1:66
	s_waitcnt vmcnt(4)
	ds_write2_b32 v37, v87, v89 offset0:132 offset1:198
	v_add_u32_e32 v4, 0x400, v37
	s_waitcnt vmcnt(2)
	ds_write2_b32 v4, v91, v93 offset0:8 offset1:74
	s_waitcnt vmcnt(0)
	ds_write2_b32 v4, v95, v97 offset0:140 offset1:206
	s_waitcnt lgkmcnt(0)
	ds_read2_b32 v[102:103], v119 offset0:33 offset1:41
	ds_read2_b32 v[158:159], v119 offset1:8
	ds_read2_b32 v[160:161], v119 offset0:66 offset1:74
	ds_read2_b32 v[162:163], v119 offset0:99 offset1:107
	ds_read2_b32 v[164:165], v119 offset0:132 offset1:140
	ds_read2_b32 v[166:167], v119 offset0:165 offset1:173
	ds_read2_b32 v[168:169], v119 offset0:198 offset1:206
	ds_read2_b32 v[170:171], v119 offset0:231 offset1:239
	v_or_b32_e32 v4, s6, v118
	v_lshlrev_b32_e32 v4, 11, v4
	s_waitcnt lgkmcnt(6)
	v_cvt_pk_bf16_f32 v154, v158, v102
	s_waitcnt lgkmcnt(4)
	v_cvt_pk_bf16_f32 v155, v160, v162
	s_waitcnt lgkmcnt(2)
	v_cvt_pk_bf16_f32 v156, v164, v166
	s_waitcnt lgkmcnt(0)
	v_cvt_pk_bf16_f32 v157, v168, v170
	v_lshl_add_u64 v[174:175], v[172:173], 0, v[4:5]
	global_store_dwordx4 v[174:175], v[154:157], off
	v_or_b32_e32 v4, s6, v120
	v_lshlrev_b32_e32 v4, 11, v4
	v_cvt_pk_bf16_f32 v154, v159, v103
	v_cvt_pk_bf16_f32 v155, v161, v163
	v_cvt_pk_bf16_f32 v156, v165, v167
	v_cvt_pk_bf16_f32 v157, v169, v171
	ds_read2_b32 v[158:159], v119 offset0:49 offset1:57
	ds_read2_b32 v[160:161], v119 offset0:16 offset1:24
	ds_read2_b32 v[162:163], v119 offset0:82 offset1:90
	ds_read2_b32 v[164:165], v119 offset0:115 offset1:123
	ds_read2_b32 v[166:167], v119 offset0:148 offset1:156
	ds_read2_b32 v[168:169], v119 offset0:181 offset1:189
	ds_read2_b32 v[170:171], v119 offset0:214 offset1:222
	ds_read2_b32 v[174:175], v119 offset0:247 offset1:255
	v_lshl_add_u64 v[102:103], v[172:173], 0, v[4:5]
	v_or_b32_e32 v4, s6, v121
	v_lshlrev_b32_e32 v4, 11, v4
	global_store_dwordx4 v[102:103], v[154:157], off
	v_lshl_add_u64 v[102:103], v[172:173], 0, v[4:5]
	v_or_b32_e32 v4, s6, v122
	s_waitcnt lgkmcnt(6)
	v_cvt_pk_bf16_f32 v154, v160, v158
	s_waitcnt lgkmcnt(4)
	v_cvt_pk_bf16_f32 v155, v162, v164
	s_waitcnt lgkmcnt(2)
	v_cvt_pk_bf16_f32 v156, v166, v168
	s_waitcnt lgkmcnt(0)
	v_cvt_pk_bf16_f32 v157, v170, v174
	v_lshlrev_b32_e32 v4, 11, v4
	global_store_dwordx4 v[102:103], v[154:157], off
	v_lshl_add_u64 v[102:103], v[172:173], 0, v[4:5]
	s_nop 0
	v_cvt_pk_bf16_f32 v154, v161, v159
	v_cvt_pk_bf16_f32 v155, v163, v165
	v_cvt_pk_bf16_f32 v156, v167, v169
	v_cvt_pk_bf16_f32 v157, v171, v175
	global_store_dwordx4 v[102:103], v[154:157], off
	s_waitcnt lgkmcnt(0)

.LBB0_95:
	s_andn2_b64 vcc, exec, s[6:7]
	s_cbranch_vccnz .LBB0_8
	s_ashr_i32 s2, s21, 31
	s_lshr_b32 s2, s2, 26
	s_add_i32 s11, s21, s2
	s_lshl_b32 s2, s11, 5
	s_and_b32 s2, s2, 0xfffff800
	s_sub_i32 s10, s13, s2
	s_and_b32 s6, s11, 0xffffffc0
	s_ashr_i32 s11, s10, 31
	v_lshl_add_u64 v[102:103], s[10:11], 2, v[34:35]
	v_or_b32_e32 v4, s6, v3
	v_lshlrev_b32_e32 v4, 13, v4
	v_lshl_add_u64 v[154:155], v[102:103], 0, v[4:5]
	v_or_b32_e32 v4, s6, v105
	v_lshlrev_b32_e32 v4, 13, v4
	v_lshl_add_u64 v[156:157], v[102:103], 0, v[4:5]
	v_or_b32_e32 v4, s6, v123
	v_lshlrev_b32_e32 v4, 13, v4
	v_lshl_add_u64 v[158:159], v[102:103], 0, v[4:5]
	v_or_b32_e32 v4, s6, v124
	v_lshlrev_b32_e32 v4, 13, v4
	v_lshl_add_u64 v[160:161], v[102:103], 0, v[4:5]
	v_or_b32_e32 v4, s6, v125
	v_lshlrev_b32_e32 v4, 13, v4
	v_lshl_add_u64 v[162:163], v[102:103], 0, v[4:5]
	v_or_b32_e32 v4, s6, v126
	v_lshlrev_b32_e32 v4, 13, v4
	v_lshl_add_u64 v[164:165], v[102:103], 0, v[4:5]
	v_or_b32_e32 v4, s6, v127
	v_lshlrev_b32_e32 v4, 13, v4
	v_lshl_add_u64 v[166:167], v[102:103], 0, v[4:5]
	v_or_b32_e32 v4, s6, v128
	v_lshlrev_b32_e32 v4, 13, v4
	v_lshl_add_u64 v[168:169], v[102:103], 0, v[4:5]
	global_load_dword v37, v[154:155], off nt
	global_load_dword v39, v[156:157], off nt
	global_load_dword v41, v[158:159], off nt
	global_load_dword v43, v[160:161], off nt
	global_load_dword v45, v[162:163], off nt
	global_load_dword v47, v[164:165], off nt
	global_load_dword v49, v[166:167], off nt
	global_load_dword v51, v[168:169], off nt
	v_or_b32_e32 v4, s6, v129
	v_lshlrev_b32_e32 v4, 13, v4
	v_lshl_add_u64 v[154:155], v[102:103], 0, v[4:5]
	v_or_b32_e32 v4, s6, v130
	v_lshlrev_b32_e32 v4, 13, v4
	v_lshl_add_u64 v[156:157], v[102:103], 0, v[4:5]
	v_or_b32_e32 v4, s6, v131
	v_lshlrev_b32_e32 v4, 13, v4
	v_lshl_add_u64 v[158:159], v[102:103], 0, v[4:5]
	v_or_b32_e32 v4, s6, v132
	v_lshlrev_b32_e32 v4, 13, v4
	v_lshl_add_u64 v[160:161], v[102:103], 0, v[4:5]
	v_or_b32_e32 v4, s6, v133
	v_lshlrev_b32_e32 v4, 13, v4
	v_lshl_add_u64 v[162:163], v[102:103], 0, v[4:5]
	v_or_b32_e32 v4, s6, v134
	v_lshlrev_b32_e32 v4, 13, v4
	v_lshl_add_u64 v[164:165], v[102:103], 0, v[4:5]
	v_or_b32_e32 v4, s6, v135
	v_lshlrev_b32_e32 v4, 13, v4
	v_lshl_add_u64 v[166:167], v[102:103], 0, v[4:5]
	v_or_b32_e32 v4, s6, v136
	v_lshlrev_b32_e32 v4, 13, v4
	v_lshl_add_u64 v[168:169], v[102:103], 0, v[4:5]
	global_load_dword v53, v[154:155], off nt
	global_load_dword v55, v[156:157], off nt
	global_load_dword v57, v[158:159], off nt
	global_load_dword v59, v[160:161], off nt
	global_load_dword v61, v[162:163], off nt
	global_load_dword v63, v[164:165], off nt
	global_load_dword v65, v[166:167], off nt
	global_load_dword v67, v[168:169], off nt
	v_or_b32_e32 v4, s6, v137
	v_lshlrev_b32_e32 v4, 13, v4
	v_lshl_add_u64 v[154:155], v[102:103], 0, v[4:5]
	v_or_b32_e32 v4, s6, v138
	v_lshlrev_b32_e32 v4, 13, v4
	v_lshl_add_u64 v[156:157], v[102:103], 0, v[4:5]
	v_or_b32_e32 v4, s6, v139
	v_lshlrev_b32_e32 v4, 13, v4
	v_lshl_add_u64 v[158:159], v[102:103], 0, v[4:5]
	v_or_b32_e32 v4, s6, v140
	v_lshlrev_b32_e32 v4, 13, v4
	v_lshl_add_u64 v[160:161], v[102:103], 0, v[4:5]
	v_or_b32_e32 v4, s6, v141
	v_lshlrev_b32_e32 v4, 13, v4
	v_lshl_add_u64 v[162:163], v[102:103], 0, v[4:5]
	v_or_b32_e32 v4, s6, v142
	v_lshlrev_b32_e32 v4, 13, v4
	v_lshl_add_u64 v[164:165], v[102:103], 0, v[4:5]
	v_or_b32_e32 v4, s6, v143
	v_lshlrev_b32_e32 v4, 13, v4
	v_lshl_add_u64 v[166:167], v[102:103], 0, v[4:5]
	v_or_b32_e32 v4, s6, v144
	v_lshlrev_b32_e32 v4, 13, v4
	v_lshl_add_u64 v[168:169], v[102:103], 0, v[4:5]
	global_load_dword v69, v[154:155], off nt
	global_load_dword v71, v[156:157], off nt
	global_load_dword v73, v[158:159], off nt
	global_load_dword v75, v[160:161], off nt
	global_load_dword v77, v[162:163], off nt
	global_load_dword v79, v[164:165], off nt
	global_load_dword v81, v[166:167], off nt
	global_load_dword v83, v[168:169], off nt
	v_or_b32_e32 v4, s6, v145
	v_lshlrev_b32_e32 v4, 13, v4
	v_lshl_add_u64 v[154:155], v[102:103], 0, v[4:5]
	v_or_b32_e32 v4, s6, v146
	v_lshlrev_b32_e32 v4, 13, v4
	v_lshl_add_u64 v[156:157], v[102:103], 0, v[4:5]
	v_or_b32_e32 v4, s6, v147
	v_lshlrev_b32_e32 v4, 13, v4
	v_lshl_add_u64 v[158:159], v[102:103], 0, v[4:5]
	v_or_b32_e32 v4, s6, v148
	v_lshlrev_b32_e32 v4, 13, v4
	v_lshl_add_u64 v[160:161], v[102:103], 0, v[4:5]
	v_or_b32_e32 v4, s6, v149
	v_lshlrev_b32_e32 v4, 13, v4
	v_lshl_add_u64 v[162:163], v[102:103], 0, v[4:5]
	v_or_b32_e32 v4, s6, v150
	v_lshlrev_b32_e32 v4, 13, v4
	v_lshl_add_u64 v[164:165], v[102:103], 0, v[4:5]
	v_or_b32_e32 v4, s6, v151
	v_lshlrev_b32_e32 v4, 13, v4
	v_lshl_add_u64 v[166:167], v[102:103], 0, v[4:5]
	v_or_b32_e32 v4, s6, v152
	v_lshlrev_b32_e32 v4, 13, v4
	v_lshl_add_u64 v[168:169], v[102:103], 0, v[4:5]
	global_load_dword v4, v[154:155], off nt
	global_load_dword v85, v[156:157], off nt
	global_load_dword v87, v[158:159], off nt
	global_load_dword v89, v[160:161], off nt
	global_load_dword v91, v[162:163], off nt
	global_load_dword v93, v[164:165], off nt
	global_load_dword v95, v[166:167], off nt
	global_load_dword v97, v[168:169], off nt
	v_add_u32_e32 v99, v104, v153
	s_waitcnt vmcnt(30)
	ds_write2_b32 v99, v37, v39 offset1:66
	s_waitcnt vmcnt(28)
	ds_write2_b32 v99, v41, v43 offset0:132 offset1:198
	v_add_u32_e32 v37, 0x400, v99
	s_waitcnt vmcnt(26)
	ds_write2_b32 v37, v45, v47 offset0:8 offset1:74
	v_add_u32_e32 v37, v104, v108
	s_waitcnt vmcnt(24)
	ds_write2_b32 v37, v49, v51 offset1:66
	s_waitcnt vmcnt(22)
	ds_write2_b32 v37, v53, v55 offset0:132 offset1:198
	v_add_u32_e32 v37, 0x400, v37
	s_waitcnt vmcnt(20)
	ds_write2_b32 v37, v57, v59 offset0:8 offset1:74
	v_add_u32_e32 v37, v104, v111
	s_waitcnt vmcnt(18)
	ds_write2_b32 v37, v61, v63 offset1:66
	s_waitcnt vmcnt(16)
	ds_write2_b32 v37, v65, v67 offset0:132 offset1:198
	v_add_u32_e32 v37, 0x400, v37
	s_waitcnt vmcnt(14)
	ds_write2_b32 v37, v69, v71 offset0:8 offset1:74
	v_add_u32_e32 v37, v104, v114
	s_waitcnt vmcnt(12)
	ds_write2_b32 v37, v73, v75 offset1:66
	s_waitcnt vmcnt(10)
	ds_write2_b32 v37, v77, v79 offset0:132 offset1:198
	v_add_u32_e32 v37, 0x400, v37
	s_waitcnt vmcnt(8)
	ds_write2_b32 v37, v81, v83 offset0:8 offset1:74
	v_add_u32_e32 v37, v104, v117
	s_waitcnt vmcnt(6)
	ds_write2_b32 v37, v4, v85 offset1:66
	s_waitcnt vmcnt(4)
	ds_write2_b32 v37, v87, v89 offset0:132 offset1:198
	v_add_u32_e32 v4, 0x400, v37
	s_waitcnt vmcnt(2)
	ds_write2_b32 v4, v91, v93 offset0:8 offset1:74
	s_waitcnt vmcnt(0)
	ds_write2_b32 v4, v95, v97 offset0:140 offset1:206
	s_branch .LBB0_7

.LBB0_216:
	v_ashrrev_i64 v[2:3], 7, v[74:75]
	s_mov_b64 s[0:1], 0x3fff
	v_cmp_gt_i64_e32 vcc, s[28:29], v[2:3]
	v_cmp_lt_i64_e64 s[0:1], s[0:1], v[2:3]
	s_and_saveexec_b64 s[4:5], s[0:1]
	s_xor_b64 s[0:1], exec, s[4:5]
	v_add_u32_e32 v1, 0xffffc000, v2
	v_lshrrev_b32_e32 v1, 3, v1
	v_add_u32_e32 v4, 2, v1
	s_andn2_saveexec_b64 s[0:1], s[0:1]
	v_ashrrev_i32_e32 v1, 31, v2
	v_lshrrev_b32_e32 v1, 19, v1
	v_add_u32_e32 v1, v2, v1
	v_ashrrev_i32_e32 v4, 13, v1
	s_or_b64 exec, exec, s[0:1]
	v_readlane_b32 s52, v241, 52
	v_readlane_b32 s53, v241, 53
	v_readlane_b32 s54, v241, 54
	v_readlane_b32 s55, v241, 55
	s_mov_b64 s[44:45], s[52:53]
	v_lshlrev_b64 v[2:3], 12, v[2:3]
	s_mov_b64 s[46:47], s[54:55]
	v_lshl_add_u64 v[6:7], s[46:47], 0, v[2:3]
	v_and_b32_e32 v1, 0x3f8, v98
	v_lshl_add_u64 v[6:7], v[6:7], 0, s[30:31]
	v_lshl_add_u64 v[2:3], s[44:45], 0, v[2:3]
	v_cndmask_b32_e32 v3, v7, v3, vcc
	v_cndmask_b32_e32 v2, v6, v2, vcc
	v_lshlrev_b32_e32 v100, 2, v1
	v_lshl_add_u64 v[6:7], v[2:3], 0, v[100:101]
	v_mad_i64_i32 v[2:3], s[0:1], v4, s33, v[102:103]
	v_lshl_add_u64 v[18:19], v[2:3], 0, v[100:101]
	global_load_dwordx4 v[2:5], v[6:7], off offset:16 nt
	global_load_dwordx4 v[10:13], v[6:7], off nt
	v_add_co_u32_e32 v6, vcc, s48, v18
	v_lshl_add_u64 v[8:9], v[18:19], 0, s[34:35]
	s_nop 0
	v_addc_co_u32_e32 v7, vcc, 0, v19, vcc
	global_load_dwordx4 v[26:29], v[6:7], off
	global_load_dwordx4 v[14:17], v[8:9], off offset:16
	s_nop 0
	global_load_dwordx4 v[6:9], v[18:19], off offset:16
	s_nop 0
	global_load_dwordx4 v[18:21], v[18:19], off
	v_lshl_add_u64 v[42:43], s[10:11], 0, v[74:75]
	v_cmp_gt_i64_e64 s[0:1], s[8:9], v[42:43]
	v_readlane_b32 s56, v241, 56
	v_readlane_b32 s57, v241, 57
	v_cndmask_b32_e64 v23, v75, v43, s[0:1]
	v_cndmask_b32_e64 v22, v74, v42, s[0:1]
	v_ashrrev_i64 v[24:25], 7, v[22:23]
	v_cmp_lt_i32_e32 vcc, s49, v24
	v_readlane_b32 s58, v241, 58
	v_readlane_b32 s59, v241, 59
	v_readlane_b32 s60, v241, 60
	v_readlane_b32 s61, v241, 61
	v_readlane_b32 s62, v241, 62
	v_readlane_b32 s63, v241, 63
	v_readlane_b32 s64, v240, 0
	v_readlane_b32 s65, v240, 1
	v_readlane_b32 s66, v240, 2
	v_readlane_b32 s67, v240, 3
	s_and_saveexec_b64 s[4:5], vcc
	s_xor_b64 s[4:5], exec, s[4:5]
	v_add_u32_e32 v23, 0xffffc000, v24
	v_lshrrev_b32_e32 v23, 3, v23
	v_add_u32_e32 v23, 2, v23
	s_andn2_saveexec_b64 s[4:5], s[4:5]
	v_ashrrev_i32_e32 v23, 31, v24
	v_lshrrev_b32_e32 v23, 19, v23
	v_add_u32_e32 v23, v24, v23
	v_ashrrev_i32_e32 v23, 13, v23
	s_or_b64 exec, exec, s[4:5]
	v_readlane_b32 s52, v241, 52
	v_readlane_b32 s53, v241, 53
	v_readlane_b32 s54, v241, 54
	v_readlane_b32 s55, v241, 55
	s_mov_b64 s[44:45], s[52:53]
	v_lshlrev_b64 v[30:31], 12, v[24:25]
	s_mov_b64 s[46:47], s[54:55]
	v_lshl_add_u64 v[32:33], s[44:45], 0, v[30:31]
	v_lshl_add_u64 v[30:31], s[46:47], 0, v[30:31]
	v_lshl_add_u64 v[30:31], v[30:31], 0, s[30:31]
	v_cmp_gt_i64_e32 vcc, s[28:29], v[24:25]
	v_lshlrev_b32_e32 v22, 5, v22
	v_and_b32_e32 v100, 0xfe0, v22
	v_cndmask_b32_e32 v25, v31, v33, vcc
	v_cndmask_b32_e32 v24, v30, v32, vcc
	v_lshl_add_u64 v[30:31], v[24:25], 0, v[100:101]
	v_mov_b64_e32 v[24:25], s[90:91]
	v_mad_i64_i32 v[22:23], s[4:5], v23, s33, v[24:25]
	v_lshl_add_u64 v[44:45], v[22:23], 0, v[100:101]
	global_load_dwordx4 v[22:25], v[30:31], off offset:16 nt
	global_load_dwordx4 v[34:37], v[30:31], off nt
	v_add_co_u32_e32 v30, vcc, s48, v44
	v_lshl_add_u64 v[32:33], v[44:45], 0, s[34:35]
	s_nop 0
	v_addc_co_u32_e32 v31, vcc, 0, v45, vcc
	global_load_dwordx4 v[50:53], v[30:31], off
	global_load_dwordx4 v[38:41], v[32:33], off offset:16
	s_nop 0
	global_load_dwordx4 v[30:33], v[44:45], off offset:16
	global_load_dwordx4 v[46:49], v[44:45], off
	v_lshl_add_u64 v[76:77], s[10:11], 0, v[42:43]
	v_cmp_gt_i64_e64 s[4:5], s[8:9], v[76:77]
	v_readlane_b32 s56, v241, 56
	v_readlane_b32 s57, v241, 57
	v_cndmask_b32_e64 v43, v75, v77, s[4:5]
	v_cndmask_b32_e64 v42, v74, v76, s[4:5]
	v_ashrrev_i64 v[44:45], 7, v[42:43]
	v_cmp_lt_i32_e32 vcc, s49, v44
	v_readlane_b32 s58, v241, 58
	v_readlane_b32 s59, v241, 59
	v_readlane_b32 s60, v241, 60
	v_readlane_b32 s61, v241, 61
	v_readlane_b32 s62, v241, 62
	v_readlane_b32 s63, v241, 63
	v_readlane_b32 s64, v240, 0
	v_readlane_b32 s65, v240, 1
	v_readlane_b32 s66, v240, 2
	v_readlane_b32 s67, v240, 3
	s_and_saveexec_b64 s[6:7], vcc
	s_xor_b64 s[6:7], exec, s[6:7]
	v_add_u32_e32 v43, 0xffffc000, v44
	v_lshrrev_b32_e32 v43, 3, v43
	v_add_u32_e32 v43, 2, v43
	s_andn2_saveexec_b64 s[6:7], s[6:7]
	v_ashrrev_i32_e32 v43, 31, v44
	v_lshrrev_b32_e32 v43, 19, v43
	v_add_u32_e32 v43, v44, v43
	v_ashrrev_i32_e32 v43, 13, v43
	s_or_b64 exec, exec, s[6:7]
	v_readlane_b32 s52, v241, 52
	v_readlane_b32 s53, v241, 53
	v_readlane_b32 s54, v241, 54
	v_readlane_b32 s55, v241, 55
	s_mov_b64 s[44:45], s[52:53]
	v_lshlrev_b64 v[54:55], 12, v[44:45]
	s_mov_b64 s[46:47], s[54:55]
	v_lshl_add_u64 v[56:57], s[44:45], 0, v[54:55]
	v_lshl_add_u64 v[54:55], s[46:47], 0, v[54:55]
	v_lshl_add_u64 v[54:55], v[54:55], 0, s[30:31]
	v_cmp_gt_i64_e32 vcc, s[28:29], v[44:45]
	v_lshlrev_b32_e32 v42, 5, v42
	v_and_b32_e32 v100, 0xfe0, v42
	v_cndmask_b32_e32 v45, v55, v57, vcc
	v_cndmask_b32_e32 v44, v54, v56, vcc
	v_lshl_add_u64 v[54:55], v[44:45], 0, v[100:101]
	v_mov_b64_e32 v[44:45], s[90:91]
	v_mad_i64_i32 v[42:43], s[6:7], v43, s33, v[44:45]
	v_lshl_add_u64 v[66:67], v[42:43], 0, v[100:101]
	global_load_dwordx4 v[42:45], v[54:55], off offset:16 nt
	global_load_dwordx4 v[58:61], v[54:55], off nt
	v_add_co_u32_e32 v54, vcc, s48, v66
	v_lshl_add_u64 v[56:57], v[66:67], 0, s[34:35]
	s_nop 0
	v_addc_co_u32_e32 v55, vcc, 0, v67, vcc
	global_load_dwordx4 v[70:73], v[54:55], off
	global_load_dwordx4 v[62:65], v[56:57], off offset:16
	s_nop 0
	global_load_dwordx4 v[54:57], v[66:67], off offset:16
	s_nop 0
	global_load_dwordx4 v[66:69], v[66:67], off
	v_lshl_add_u64 v[104:105], s[10:11], 0, v[76:77]
	v_cmp_gt_i64_e32 vcc, s[8:9], v[104:105]
	v_readlane_b32 s56, v241, 56
	v_readlane_b32 s57, v241, 57
	v_cndmask_b32_e32 v75, v75, v105, vcc
	v_cndmask_b32_e32 v74, v74, v104, vcc
	v_ashrrev_i64 v[76:77], 7, v[74:75]
	v_cmp_lt_i32_e64 s[6:7], s49, v76
	v_readlane_b32 s58, v241, 58
	v_readlane_b32 s59, v241, 59
	v_readlane_b32 s60, v241, 60
	v_readlane_b32 s61, v241, 61
	v_readlane_b32 s62, v241, 62
	v_readlane_b32 s63, v241, 63
	v_readlane_b32 s64, v240, 0
	v_readlane_b32 s65, v240, 1
	v_readlane_b32 s66, v240, 2
	v_readlane_b32 s67, v240, 3
	s_and_saveexec_b64 s[50:51], s[6:7]
	s_xor_b64 s[6:7], exec, s[50:51]
	v_add_u32_e32 v75, 0xffffc000, v76
	v_lshrrev_b32_e32 v75, 3, v75
	v_add_u32_e32 v75, 2, v75
	s_andn2_saveexec_b64 s[6:7], s[6:7]
	v_ashrrev_i32_e32 v75, 31, v76
	v_lshrrev_b32_e32 v75, 19, v75
	v_add_u32_e32 v75, v76, v75
	v_ashrrev_i32_e32 v75, 13, v75
	s_or_b64 exec, exec, s[6:7]
	v_readlane_b32 s52, v241, 52
	v_readlane_b32 s53, v241, 53
	v_readlane_b32 s54, v241, 54
	v_readlane_b32 s55, v241, 55
	s_mov_b64 s[44:45], s[52:53]
	s_waitcnt vmcnt(20)
	v_lshlrev_b64 v[78:79], 12, v[76:77]
	s_mov_b64 s[46:47], s[54:55]
	v_lshl_add_u64 v[80:81], s[44:45], 0, v[78:79]
	v_lshl_add_u64 v[78:79], s[46:47], 0, v[78:79]
	v_lshl_add_u64 v[78:79], v[78:79], 0, s[30:31]
	v_cmp_gt_i64_e64 s[6:7], s[28:29], v[76:77]
	v_lshlrev_b32_e32 v74, 5, v74
	v_and_b32_e32 v100, 0xfe0, v74
	v_cndmask_b32_e64 v77, v79, v81, s[6:7]
	v_cndmask_b32_e64 v76, v78, v80, s[6:7]
	v_lshl_add_u64 v[78:79], v[76:77], 0, v[100:101]
	v_mov_b64_e32 v[76:77], s[90:91]
	v_mad_i64_i32 v[74:75], s[6:7], v75, s33, v[76:77]
	s_waitcnt vmcnt(19)
	v_lshl_add_u64 v[90:91], v[74:75], 0, v[100:101]
	global_load_dwordx4 v[74:77], v[78:79], off offset:16 nt
	global_load_dwordx4 v[86:89], v[78:79], off nt
	v_add_co_u32_e64 v78, s[6:7], s48, v90
	v_lshl_add_u64 v[80:81], v[90:91], 0, s[34:35]
	s_nop 0
	v_addc_co_u32_e64 v79, s[6:7], 0, v91, s[6:7]
	global_load_dwordx4 v[94:97], v[78:79], off
	global_load_dwordx4 v[82:85], v[80:81], off offset:16
	s_nop 0
	global_load_dwordx4 v[78:81], v[90:91], off offset:16
	s_nop 0
	global_load_dwordx4 v[90:93], v[90:91], off
	v_and_b32_e32 v107, 0x7fffffff, v99
	v_and_b32_e32 v106, 0xfffffc00, v98
	s_waitcnt vmcnt(21)
	v_pk_add_f32 v[28:29], v[28:29], 1.0 op_sel_hi:[1,0]
	v_pk_add_f32 v[26:27], v[26:27], 1.0 op_sel_hi:[1,0]
	s_waitcnt vmcnt(20)
	v_pk_add_f32 v[14:15], v[14:15], 1.0 op_sel_hi:[1,0]
	v_pk_add_f32 v[16:17], v[16:17], 1.0 op_sel_hi:[1,0]
	v_lshl_add_u64 v[106:107], v[106:107], 1, s[82:83]
	v_lshlrev_b32_e32 v100, 1, v1
	s_waitcnt vmcnt(18)
	v_pk_fma_f32 v[12:13], v[12:13], v[28:29], v[20:21]
	v_pk_fma_f32 v[10:11], v[10:11], v[26:27], v[18:19]
	v_pk_fma_f32 v[8:9], v[4:5], v[16:17], v[8:9]
	v_pk_fma_f32 v[4:5], v[2:3], v[14:15], v[6:7]
	v_lshl_add_u64 v[106:107], v[106:107], 0, v[100:101]
	v_cvt_pk_bf16_f32 v2, v10, v11
	v_cvt_pk_bf16_f32 v3, v12, v13
	v_cvt_pk_bf16_f32 v4, v4, v5
	v_cvt_pk_bf16_f32 v5, v8, v9
	v_readlane_b32 s56, v241, 56
	v_readlane_b32 s57, v241, 57
	v_readlane_b32 s58, v241, 58
	v_readlane_b32 s59, v241, 59
	v_readlane_b32 s60, v241, 60
	v_readlane_b32 s61, v241, 61
	v_readlane_b32 s62, v241, 62
	v_readlane_b32 s63, v241, 63
	v_readlane_b32 s64, v240, 0
	v_readlane_b32 s65, v240, 1
	v_readlane_b32 s66, v240, 2
	v_readlane_b32 s67, v240, 3
	global_store_dwordx4 v[106:107], v[2:5], off
	s_and_saveexec_b64 s[6:7], s[0:1]
	s_cbranch_execz .LBB0_235
	v_lshl_add_u64 v[2:3], s[24:25], 0, v[98:99]
	v_and_b32_e32 v1, 0x3f8, v2
	v_and_b32_e32 v3, 0x7fffffff, v3
	v_and_b32_e32 v2, 0xfffffc00, v2
	v_lshl_add_u64 v[2:3], v[2:3], 1, s[82:83]
	v_lshlrev_b32_e32 v100, 1, v1
	v_lshl_add_u64 v[6:7], v[2:3], 0, v[100:101]
	s_waitcnt vmcnt(16)
	v_pk_add_f32 v[2:3], v[52:53], 1.0 op_sel_hi:[1,0]
	v_pk_add_f32 v[4:5], v[50:51], 1.0 op_sel_hi:[1,0]
	s_waitcnt vmcnt(13)
	v_pk_fma_f32 v[8:9], v[36:37], v[2:3], v[48:49]
	v_pk_fma_f32 v[2:3], v[34:35], v[4:5], v[46:47]
	v_pk_add_f32 v[4:5], v[38:39], 1.0 op_sel_hi:[1,0]
	v_pk_add_f32 v[10:11], v[40:41], 1.0 op_sel_hi:[1,0]
	v_pk_fma_f32 v[4:5], v[22:23], v[4:5], v[30:31]
	v_pk_fma_f32 v[10:11], v[24:25], v[10:11], v[32:33]
	v_cvt_pk_bf16_f32 v2, v2, v3
	v_cvt_pk_bf16_f32 v3, v8, v9
	v_cvt_pk_bf16_f32 v4, v4, v5
	v_cvt_pk_bf16_f32 v5, v10, v11
	global_store_dwordx4 v[6:7], v[2:5], off
	s_or_b64 exec, exec, s[6:7]
	s_and_saveexec_b64 s[0:1], s[4:5]
	s_cbranch_execnz .LBB0_236

.LBB0_743:
	s_ashr_i32 s1, s10, 31
	s_lshr_b32 s1, s1, 27
	s_add_i32 s1, s10, s1
	s_ashr_i32 s1, s1, 5
	s_lshl_b32 s0, s11, 5
	s_mul_hi_i32 s6, s1, 0x3000
	s_mulk_i32 s1, 0x3000
	s_add_u32 s27, s90, s1
	s_addc_u32 s28, s91, s6
	s_add_u32 s6, s27, 0x2000
	s_addc_u32 s7, s28, 0
	s_lshl_b32 s1, s8, 8
	v_lshrrev_b32_e32 v130, 1, v178
	s_or_b32 s0, s1, s0
	s_lshl_b32 s26, s10, 8
	v_and_or_b32 v156, v130, 24, s0
	s_add_i32 s0, s26, s44
	v_or_b32_e32 v148, s0, v179
	v_ashrrev_i32_e32 v149, 31, v148
	v_readlane_b32 s40, v241, 52
	v_ashrrev_i32_e32 v157, 31, v156
	v_lshlrev_b64 v[138:139], 12, v[148:149]
	v_readlane_b32 s41, v241, 53
	v_lshlrev_b64 v[158:159], 2, v[156:157]
	v_lshl_add_u64 v[134:135], s[6:7], 0, v[158:159]
	v_lshl_add_u64 v[138:139], s[40:41], 0, v[138:139]
	v_lshl_add_u64 v[146:147], v[138:139], 0, v[158:159]
	s_barrier
	global_load_dwordx4 v[130:133], v[134:135], off offset:16
	s_nop 0
	global_load_dwordx4 v[134:137], v[134:135], off
	s_nop 0
	global_load_dwordx4 v[138:141], v[146:147], off
	global_load_dwordx4 v[142:145], v[146:147], off offset:16
	v_or_b32_e32 v150, 16, v148
	v_ashrrev_i32_e32 v151, 31, v150
	v_lshlrev_b64 v[150:151], 12, v[150:151]
	s_mov_b32 s0, 0x3fb504f3
	v_lshl_add_u64 v[150:151], s[40:41], 0, v[150:151]
	v_lshl_add_u64 v[160:161], v[150:151], 0, v[158:159]
	v_or_b32_e32 v154, 0x80, v156
	v_ashrrev_i32_e32 v155, 31, v154
	v_readlane_b32 s42, v241, 54
	v_readlane_b32 s43, v241, 55
	v_readlane_b32 s44, v241, 56
	v_readlane_b32 s45, v241, 57
	v_readlane_b32 s46, v241, 58
	v_readlane_b32 s47, v241, 59
	v_readlane_b32 s48, v241, 60
	v_readlane_b32 s49, v241, 61
	v_readlane_b32 s50, v241, 62
	v_readlane_b32 s51, v241, 63
	v_readlane_b32 s52, v240, 0
	v_readlane_b32 s53, v240, 1
	v_readlane_b32 s54, v240, 2
	v_readlane_b32 s55, v240, 3
	s_waitcnt vmcnt(0)
	v_pk_add_f32 v[172:173], v[132:133], 1.0 op_sel_hi:[1,0]
	v_pk_add_f32 v[150:151], v[136:137], 1.0 op_sel_hi:[1,0]
	v_pk_add_f32 v[152:153], v[134:135], 1.0 op_sel_hi:[1,0]
	v_pk_add_f32 v[174:175], v[130:131], 1.0 op_sel_hi:[1,0]
	v_pk_mul_f32 v[130:131], v[140:141], s[0:1] op_sel_hi:[1,0]
	v_pk_mul_f32 v[132:133], v[138:139], s[0:1] op_sel_hi:[1,0]
	v_pk_mul_f32 v[134:135], v[144:145], s[0:1] op_sel_hi:[1,0]
	v_pk_mul_f32 v[136:137], v[142:143], s[0:1] op_sel_hi:[1,0]
	v_pk_fma_f32 v[144:145], v[128:129], v[150:151], v[130:131]
	v_pk_fma_f32 v[142:143], v[126:127], v[152:153], v[132:133]
	v_pk_fma_f32 v[140:141], v[124:125], v[172:173], v[134:135]
	v_pk_fma_f32 v[138:139], v[122:123], v[174:175], v[136:137]
	v_or_b32_e32 v130, 32, v148
	global_load_dwordx4 v[122:125], v[160:161], off nt
	global_load_dwordx4 v[126:129], v[160:161], off offset:16 nt
	v_ashrrev_i32_e32 v131, 31, v130
	v_lshlrev_b64 v[130:131], 12, v[130:131]
	v_lshl_add_u64 v[130:131], s[40:41], 0, v[130:131]
	v_lshl_add_u64 v[162:163], v[130:131], 0, v[158:159]
	s_waitcnt vmcnt(1)
	v_pk_mul_f32 v[124:125], v[124:125], s[0:1] op_sel_hi:[1,0]
	v_pk_mul_f32 v[122:123], v[122:123], s[0:1] op_sel_hi:[1,0]
	s_waitcnt vmcnt(0)
	v_pk_mul_f32 v[128:129], v[128:129], s[0:1] op_sel_hi:[1,0]
	v_pk_mul_f32 v[126:127], v[126:127], s[0:1] op_sel_hi:[1,0]
	v_pk_fma_f32 v[136:137], v[116:117], v[150:151], v[124:125]
	v_pk_fma_f32 v[134:135], v[114:115], v[152:153], v[122:123]
	v_pk_fma_f32 v[128:129], v[108:109], v[172:173], v[128:129]
	v_pk_fma_f32 v[126:127], v[106:107], v[174:175], v[126:127]
	v_or_b32_e32 v122, 48, v148
	global_load_dwordx4 v[106:109], v[162:163], off nt
	global_load_dwordx4 v[114:117], v[162:163], off offset:16 nt
	v_ashrrev_i32_e32 v123, 31, v122
	v_lshlrev_b64 v[122:123], 12, v[122:123]
	v_lshl_add_u64 v[122:123], s[40:41], 0, v[122:123]
	v_lshl_add_u64 v[166:167], v[122:123], 0, v[158:159]
	s_waitcnt vmcnt(1)
	v_pk_mul_f32 v[108:109], v[108:109], s[0:1] op_sel_hi:[1,0]
	v_pk_mul_f32 v[106:107], v[106:107], s[0:1] op_sel_hi:[1,0]
	s_waitcnt vmcnt(0)
	v_pk_mul_f32 v[116:117], v[116:117], s[0:1] op_sel_hi:[1,0]
	v_pk_mul_f32 v[114:115], v[114:115], s[0:1] op_sel_hi:[1,0]
	v_pk_fma_f32 v[132:133], v[104:105], v[150:151], v[108:109]
	v_pk_fma_f32 v[130:131], v[102:103], v[152:153], v[106:107]
	v_pk_fma_f32 v[124:125], v[100:101], v[172:173], v[116:117]
	v_pk_fma_f32 v[122:123], v[98:99], v[174:175], v[114:115]
	v_add_u32_e32 v106, 0x80, v148
	global_load_dwordx4 v[98:101], v[166:167], off nt
	global_load_dwordx4 v[102:105], v[166:167], off offset:16 nt
	v_ashrrev_i32_e32 v107, 31, v106
	v_lshlrev_b64 v[106:107], 12, v[106:107]
	v_lshl_add_u64 v[106:107], s[40:41], 0, v[106:107]
	v_lshl_add_u64 v[168:169], v[106:107], 0, v[158:159]
	s_waitcnt vmcnt(1)
	v_pk_mul_f32 v[100:101], v[100:101], s[0:1] op_sel_hi:[1,0]
	v_pk_mul_f32 v[98:99], v[98:99], s[0:1] op_sel_hi:[1,0]
	s_waitcnt vmcnt(0)
	v_pk_mul_f32 v[104:105], v[104:105], s[0:1] op_sel_hi:[1,0]
	v_pk_mul_f32 v[102:103], v[102:103], s[0:1] op_sel_hi:[1,0]
	v_pk_fma_f32 v[116:117], v[96:97], v[150:151], v[100:101]
	v_pk_fma_f32 v[114:115], v[94:95], v[152:153], v[98:99]
	v_pk_fma_f32 v[108:109], v[88:89], v[172:173], v[104:105]
	v_pk_fma_f32 v[106:107], v[86:87], v[174:175], v[102:103]
	v_add_u32_e32 v98, 0x90, v148
	global_load_dwordx4 v[86:89], v[168:169], off nt
	global_load_dwordx4 v[94:97], v[168:169], off offset:16 nt
	v_ashrrev_i32_e32 v99, 31, v98
	v_lshlrev_b64 v[98:99], 12, v[98:99]
	v_lshl_add_u64 v[98:99], s[40:41], 0, v[98:99]
	v_lshl_add_u64 v[170:171], v[98:99], 0, v[158:159]
	s_waitcnt vmcnt(1)
	v_pk_mul_f32 v[88:89], v[88:89], s[0:1] op_sel_hi:[1,0]
	v_pk_mul_f32 v[86:87], v[86:87], s[0:1] op_sel_hi:[1,0]
	s_waitcnt vmcnt(0)
	v_pk_mul_f32 v[96:97], v[96:97], s[0:1] op_sel_hi:[1,0]
	v_pk_mul_f32 v[94:95], v[94:95], s[0:1] op_sel_hi:[1,0]
	v_pk_fma_f32 v[104:105], v[80:81], v[150:151], v[88:89]
	v_pk_fma_f32 v[102:103], v[78:79], v[152:153], v[86:87]
	v_pk_fma_f32 v[100:101], v[76:77], v[172:173], v[96:97]
	v_pk_fma_f32 v[98:99], v[74:75], v[174:175], v[94:95]
	v_add_u32_e32 v86, 0xa0, v148
	global_load_dwordx4 v[74:77], v[170:171], off nt
	global_load_dwordx4 v[78:81], v[170:171], off offset:16 nt
	v_ashrrev_i32_e32 v87, 31, v86
	v_lshlrev_b64 v[86:87], 12, v[86:87]
	v_lshl_add_u64 v[86:87], s[40:41], 0, v[86:87]
	v_lshl_add_u64 v[176:177], v[86:87], 0, v[158:159]
	s_waitcnt vmcnt(1)
	v_pk_mul_f32 v[76:77], v[76:77], s[0:1] op_sel_hi:[1,0]
	v_pk_mul_f32 v[74:75], v[74:75], s[0:1] op_sel_hi:[1,0]
	s_waitcnt vmcnt(0)
	v_pk_mul_f32 v[80:81], v[80:81], s[0:1] op_sel_hi:[1,0]
	v_pk_mul_f32 v[78:79], v[78:79], s[0:1] op_sel_hi:[1,0]
	v_pk_fma_f32 v[96:97], v[72:73], v[150:151], v[76:77]
	v_pk_fma_f32 v[94:95], v[70:71], v[152:153], v[74:75]
	v_pk_fma_f32 v[88:89], v[68:69], v[172:173], v[80:81]
	v_pk_fma_f32 v[86:87], v[66:67], v[174:175], v[78:79]
	v_add_u32_e32 v74, 0xb0, v148
	global_load_dwordx4 v[66:69], v[176:177], off nt
	global_load_dwordx4 v[70:73], v[176:177], off offset:16 nt
	v_ashrrev_i32_e32 v75, 31, v74
	v_lshlrev_b64 v[74:75], 12, v[74:75]
	v_lshl_add_u64 v[74:75], s[40:41], 0, v[74:75]
	v_lshl_add_u64 v[164:165], v[74:75], 0, v[158:159]
	v_lshl_add_u64 v[148:149], v[154:155], 2, s[6:7]
	s_waitcnt vmcnt(1)
	v_pk_mul_f32 v[68:69], v[68:69], s[0:1] op_sel_hi:[1,0]
	v_pk_mul_f32 v[66:67], v[66:67], s[0:1] op_sel_hi:[1,0]
	s_waitcnt vmcnt(0)
	v_pk_mul_f32 v[72:73], v[72:73], s[0:1] op_sel_hi:[1,0]
	v_pk_mul_f32 v[70:71], v[70:71], s[0:1] op_sel_hi:[1,0]
	v_pk_fma_f32 v[80:81], v[64:65], v[150:151], v[68:69]
	v_pk_fma_f32 v[78:79], v[62:63], v[152:153], v[66:67]
	v_pk_fma_f32 v[76:77], v[60:61], v[172:173], v[72:73]
	v_pk_fma_f32 v[74:75], v[58:59], v[174:175], v[70:71]
	s_nop 0
	global_load_dwordx4 v[58:61], v[164:165], off nt
	global_load_dwordx4 v[62:65], v[164:165], off offset:16 nt
	s_waitcnt vmcnt(1)
	v_pk_mul_f32 v[60:61], v[60:61], s[0:1] op_sel_hi:[1,0]
	v_pk_mul_f32 v[58:59], v[58:59], s[0:1] op_sel_hi:[1,0]
	s_waitcnt vmcnt(0)
	v_pk_mul_f32 v[64:65], v[64:65], s[0:1] op_sel_hi:[1,0]
	v_pk_mul_f32 v[62:63], v[62:63], s[0:1] op_sel_hi:[1,0]
	v_pk_fma_f32 v[72:73], v[56:57], v[150:151], v[60:61]
	v_pk_fma_f32 v[70:71], v[54:55], v[152:153], v[58:59]
	v_pk_fma_f32 v[68:69], v[52:53], v[172:173], v[64:65]
	v_pk_fma_f32 v[66:67], v[50:51], v[174:175], v[62:63]
	s_nop 0
	global_load_dwordx4 v[50:53], v[148:149], off nt
	global_load_dwordx4 v[54:57], v[148:149], off offset:16 nt
	global_load_dwordx4 v[58:61], v[146:147], off offset:512 nt
	global_load_dwordx4 v[62:65], v[146:147], off offset:528 nt
	s_waitcnt vmcnt(3)
	v_pk_add_f32 v[146:147], v[52:53], 1.0 op_sel_hi:[1,0]
	v_pk_add_f32 v[148:149], v[50:51], 1.0 op_sel_hi:[1,0]
	s_waitcnt vmcnt(2)
	v_pk_add_f32 v[150:151], v[56:57], 1.0 op_sel_hi:[1,0]
	v_pk_add_f32 v[152:153], v[54:55], 1.0 op_sel_hi:[1,0]
	s_waitcnt vmcnt(1)
	v_pk_mul_f32 v[50:51], v[60:61], s[0:1] op_sel_hi:[1,0]
	v_pk_mul_f32 v[52:53], v[58:59], s[0:1] op_sel_hi:[1,0]
	s_waitcnt vmcnt(0)
	v_pk_mul_f32 v[54:55], v[64:65], s[0:1] op_sel_hi:[1,0]
	v_pk_mul_f32 v[56:57], v[62:63], s[0:1] op_sel_hi:[1,0]
	v_pk_fma_f32 v[64:65], v[120:121], v[146:147], v[50:51]
	v_pk_fma_f32 v[62:63], v[118:119], v[148:149], v[52:53]
	v_pk_fma_f32 v[60:61], v[112:113], v[150:151], v[54:55]
	v_pk_fma_f32 v[58:59], v[110:111], v[152:153], v[56:57]
	s_nop 0
	global_load_dwordx4 v[50:53], v[160:161], off offset:512 nt
	global_load_dwordx4 v[54:57], v[160:161], off offset:528 nt
	v_mov_b32_e32 v160, v138
	v_mov_b32_e32 v161, v141
	s_waitcnt vmcnt(1)
	v_pk_mul_f32 v[52:53], v[52:53], s[0:1] op_sel_hi:[1,0]
	v_pk_mul_f32 v[50:51], v[50:51], s[0:1] op_sel_hi:[1,0]
	s_waitcnt vmcnt(0)
	v_pk_mul_f32 v[110:111], v[56:57], s[0:1] op_sel_hi:[1,0]
	v_pk_mul_f32 v[112:113], v[54:55], s[0:1] op_sel_hi:[1,0]
	v_pk_fma_f32 v[56:57], v[92:93], v[146:147], v[52:53]
	v_pk_fma_f32 v[54:55], v[90:91], v[148:149], v[50:51]
	v_pk_fma_f32 v[52:53], v[84:85], v[150:151], v[110:111]
	v_pk_fma_f32 v[50:51], v[82:83], v[152:153], v[112:113]
	s_nop 0
	global_load_dwordx4 v[82:85], v[162:163], off offset:512 nt
	global_load_dwordx4 v[90:93], v[162:163], off offset:528 nt
	s_waitcnt vmcnt(1)
	v_pk_mul_f32 v[84:85], v[84:85], s[0:1] op_sel_hi:[1,0]
	v_pk_mul_f32 v[82:83], v[82:83], s[0:1] op_sel_hi:[1,0]
	s_waitcnt vmcnt(0)
	v_pk_mul_f32 v[92:93], v[92:93], s[0:1] op_sel_hi:[1,0]
	v_pk_mul_f32 v[90:91], v[90:91], s[0:1] op_sel_hi:[1,0]
	v_pk_fma_f32 v[48:49], v[48:49], v[146:147], v[84:85]
	v_pk_fma_f32 v[46:47], v[46:47], v[148:149], v[82:83]
	v_pk_fma_f32 v[44:45], v[44:45], v[150:151], v[92:93]
	v_pk_fma_f32 v[42:43], v[42:43], v[152:153], v[90:91]
	s_nop 0
	global_load_dwordx4 v[82:85], v[166:167], off offset:512 nt
	global_load_dwordx4 v[90:93], v[166:167], off offset:528 nt
	s_waitcnt vmcnt(1)
	v_pk_mul_f32 v[84:85], v[84:85], s[0:1] op_sel_hi:[1,0]
	v_pk_mul_f32 v[82:83], v[82:83], s[0:1] op_sel_hi:[1,0]
	s_waitcnt vmcnt(0)
	v_pk_mul_f32 v[92:93], v[92:93], s[0:1] op_sel_hi:[1,0]
	v_pk_mul_f32 v[90:91], v[90:91], s[0:1] op_sel_hi:[1,0]
	v_pk_fma_f32 v[40:41], v[40:41], v[146:147], v[84:85]
	v_pk_fma_f32 v[38:39], v[38:39], v[148:149], v[82:83]
	v_pk_fma_f32 v[36:37], v[36:37], v[150:151], v[92:93]
	v_pk_fma_f32 v[34:35], v[34:35], v[152:153], v[90:91]
	s_nop 0
	global_load_dwordx4 v[82:85], v[168:169], off offset:512 nt
	global_load_dwordx4 v[90:93], v[168:169], off offset:528 nt
	s_waitcnt vmcnt(1)
	v_pk_mul_f32 v[84:85], v[84:85], s[0:1] op_sel_hi:[1,0]
	v_pk_mul_f32 v[82:83], v[82:83], s[0:1] op_sel_hi:[1,0]
	s_waitcnt vmcnt(0)
	v_pk_mul_f32 v[92:93], v[92:93], s[0:1] op_sel_hi:[1,0]
	v_pk_mul_f32 v[90:91], v[90:91], s[0:1] op_sel_hi:[1,0]
	v_pk_fma_f32 v[32:33], v[32:33], v[146:147], v[84:85]
	v_pk_fma_f32 v[30:31], v[30:31], v[148:149], v[82:83]
	v_pk_fma_f32 v[28:29], v[28:29], v[150:151], v[92:93]
	v_pk_fma_f32 v[26:27], v[26:27], v[152:153], v[90:91]
	s_nop 0
	global_load_dwordx4 v[82:85], v[170:171], off offset:512 nt
	global_load_dwordx4 v[90:93], v[170:171], off offset:528 nt
	s_waitcnt vmcnt(1)
	v_pk_mul_f32 v[84:85], v[84:85], s[0:1] op_sel_hi:[1,0]
	v_pk_mul_f32 v[82:83], v[82:83], s[0:1] op_sel_hi:[1,0]
	s_waitcnt vmcnt(0)
	v_pk_mul_f32 v[92:93], v[92:93], s[0:1] op_sel_hi:[1,0]
	v_pk_mul_f32 v[90:91], v[90:91], s[0:1] op_sel_hi:[1,0]
	v_pk_fma_f32 v[24:25], v[24:25], v[146:147], v[84:85]
	v_pk_fma_f32 v[22:23], v[22:23], v[148:149], v[82:83]
	v_pk_fma_f32 v[20:21], v[20:21], v[150:151], v[92:93]
	v_pk_fma_f32 v[18:19], v[18:19], v[152:153], v[90:91]
	v_mbcnt_lo_u32_b32 v82, -1, 0
	global_load_dwordx4 v[90:93], v[176:177], off offset:512 nt
	global_load_dwordx4 v[110:113], v[176:177], off offset:528 nt
	v_mbcnt_hi_u32_b32 v83, -1, v82
	v_and_b32_e32 v84, 64, v83
	v_add_u32_e32 v162, 64, v84
	v_mov_b32_e32 v84, v143
	v_mov_b32_e32 v85, v144
	v_xor_b32_e32 v82, 16, v83
	v_cmp_lt_i32_e32 vcc, v82, v162
	s_waitcnt vmcnt(1)
	v_pk_mul_f32 v[92:93], v[92:93], s[0:1] op_sel_hi:[1,0]
	v_pk_mul_f32 v[90:91], v[90:91], s[0:1] op_sel_hi:[1,0]
	s_waitcnt vmcnt(0)
	v_pk_mul_f32 v[112:113], v[112:113], s[0:1] op_sel_hi:[1,0]
	v_pk_mul_f32 v[110:111], v[110:111], s[0:1] op_sel_hi:[1,0]
	v_pk_fma_f32 v[16:17], v[16:17], v[146:147], v[92:93]
	v_pk_fma_f32 v[14:15], v[14:15], v[148:149], v[90:91]
	v_pk_fma_f32 v[12:13], v[12:13], v[150:151], v[112:113]
	v_pk_fma_f32 v[10:11], v[10:11], v[152:153], v[110:111]
	v_mov_b32_e32 v90, v142
	global_load_dwordx4 v[110:113], v[164:165], off offset:528 nt
	global_load_dwordx4 v[118:121], v[164:165], off offset:512 nt
	v_mov_b32_e32 v91, v145
	v_mov_b32_e32 v92, v139
	v_mov_b32_e32 v93, v140
	v_pk_add_f32 v[84:85], v[84:85], v[90:91]
	v_pk_add_f32 v[90:91], v[92:93], v[160:161]
	v_add_f32_e32 v92, v84, v85
	v_pk_add_f32 v[84:85], v[90:91], v[90:91] op_sel_hi:[0,1]
	v_add_f32_e32 v91, 0, v92
	v_add_f32_e32 v93, v62, v63
	v_add_f32_e32 v161, v64, v65
	v_mov_b32_e32 v84, v58
	v_mov_b32_e32 v90, v59
	v_mov_b32_e32 v92, v60
	v_mov_b32_e32 v160, v61
	v_pk_add_f32 v[84:85], v[84:85], v[90:91]
	v_pk_add_f32 v[90:91], v[92:93], v[160:161]
	v_cndmask_b32_e32 v82, v83, v82, vcc
	v_pk_add_f32 v[84:85], v[84:85], v[90:91]
	v_lshlrev_b32_e32 v82, 2, v82
	v_add_f32_e32 v84, v84, v85
	ds_bpermute_b32 v85, v82, v84
	v_xor_b32_e32 v90, 32, v83
	v_cmp_lt_i32_e32 vcc, v90, v162
	s_waitcnt lgkmcnt(0)
	v_add_f32_e32 v84, v84, v85
	v_cndmask_b32_e32 v83, v83, v90, vcc
	v_lshlrev_b32_e32 v83, 2, v83
	ds_bpermute_b32 v85, v83, v84
	s_waitcnt lgkmcnt(0)
	v_add_f32_e32 v85, v84, v85
	v_fmamk_f32 v90, v85, 0xbc800000, v145
	v_fmamk_f32 v92, v85, 0xbc800000, v143
	v_fmamk_f32 v160, v85, 0xbc800000, v141
	v_fmamk_f32 v162, v85, 0xbc800000, v139
	v_fmamk_f32 v84, v85, 0xbc800000, v144
	v_fmamk_f32 v91, v85, 0xbc800000, v142
	v_fmamk_f32 v93, v85, 0xbc800000, v140
	v_fmamk_f32 v161, v85, 0xbc800000, v138
	v_fmamk_f32 v164, v85, 0xbc800000, v65
	v_fmamk_f32 v166, v85, 0xbc800000, v63
	v_mul_f32_e32 v92, v92, v92
	v_mul_f32_e32 v90, v90, v90
	v_mul_f32_e32 v162, v162, v162
	v_mul_f32_e32 v160, v160, v160
	v_fmamk_f32 v163, v85, 0xbc800000, v64
	v_fmamk_f32 v165, v85, 0xbc800000, v62
	v_fmamk_f32 v168, v85, 0xbc800000, v61
	v_fmamk_f32 v170, v85, 0xbc800000, v59
	v_mul_f32_e32 v166, v166, v166
	v_mul_f32_e32 v164, v164, v164
	v_fmac_f32_e32 v92, v91, v91
	v_fmac_f32_e32 v90, v84, v84
	v_fmac_f32_e32 v162, v161, v161
	v_fmac_f32_e32 v160, v93, v93
	v_fmamk_f32 v167, v85, 0xbc800000, v60
	v_fmamk_f32 v169, v85, 0xbc800000, v58
	v_mul_f32_e32 v170, v170, v170
	v_mul_f32_e32 v168, v168, v168
	v_fmac_f32_e32 v166, v165, v165
	v_fmac_f32_e32 v164, v163, v163
	v_add_f32_e32 v84, v92, v90
	v_add_f32_e32 v90, v162, v160
	v_fmac_f32_e32 v170, v169, v169
	v_fmac_f32_e32 v168, v167, v167
	v_add_f32_e32 v91, v166, v164
	v_add_f32_e32 v84, v84, v90
	v_add_f32_e32 v92, v170, v168
	v_add_f32_e32 v84, v91, v84
	v_add_f32_e32 v90, v92, v84
	ds_bpermute_b32 v91, v82, v90
	v_and_b32_e32 v84, 63, v178
	v_cmp_gt_u32_e32 vcc, 16, v84
	s_waitcnt lgkmcnt(0)
	v_add_f32_e32 v90, v90, v91
	ds_bpermute_b32 v91, v83, v90
	s_waitcnt vmcnt(0)
	v_pk_mul_f32 v[92:93], v[120:121], s[0:1] op_sel_hi:[1,0]
	v_pk_mul_f32 v[118:119], v[118:119], s[0:1] op_sel_hi:[1,0]
	v_pk_mul_f32 v[112:113], v[112:113], s[0:1] op_sel_hi:[1,0]
	v_pk_mul_f32 v[110:111], v[110:111], s[0:1] op_sel_hi:[1,0]
	v_pk_fma_f32 v[8:9], v[8:9], v[146:147], v[92:93]
	v_pk_fma_f32 v[6:7], v[6:7], v[148:149], v[118:119]
	v_pk_fma_f32 v[4:5], v[4:5], v[150:151], v[112:113]
	v_pk_fma_f32 v[2:3], v[2:3], v[152:153], v[110:111]
	s_lshl_b32 s0, s11, 3
	s_add_i32 s6, s0, 0
	s_and_saveexec_b64 s[0:1], vcc
	s_cbranch_execz .LBB0_745
	s_lshl_b32 s7, s39, 11
	s_add_i32 s7, s6, s7
	v_mul_f32_e32 v92, 0x3c800000, v85
	v_lshl_add_u32 v85, v179, 5, s7
	s_waitcnt lgkmcnt(0)
	v_add_f32_e32 v93, v90, v91
	ds_write_b64 v85, v[92:93]
